# P7 GEMM k-loop: LDS-DMA for k+2 issued mid k-step after a fragment-complete barrier (1.5 k-steps of flight time)
# speedup vs baseline: 1.1241x; 1.0072x over previous
.LBB0_212:
	s_andn2_saveexec_b64 s[56:57], s[68:69]
	s_cbranch_execz .LBB0_161
	v_add_u32_e32 v0, 0xfffffc00, v1
	s_mov_b32 s6, 0xfc0fc0fd
	v_mul_hi_u32 v1, v0, s6
	v_lshrrev_b32_e32 v1, 10, v1
	v_mul_u32_u24_e32 v2, 0x410, v1
	v_sub_u32_e32 v2, v0, v2
	v_lshrrev_b32_e32 v67, 3, v2
	v_and_b32_e32 v2, 7, v2
	v_lshl_or_b32 v1, v1, 3, v2
	s_movk_i32 s6, 0x820
	v_add_u32_e32 v2, 8, v1
	v_cmp_gt_u32_e32 vcc, s6, v0
	v_lshlrev_b32_e32 v0, 17, v67
	v_readfirstlane_b32 s6, v91
	v_cndmask_b32_e32 v78, v2, v1, vcc
	v_mov_b32_e32 v1, v97
	v_lshlrev_b32_e32 v96, 7, v78
	v_lshlrev_b64 v[0:1], 1, v[0:1]
	v_add_u32_e32 v8, 0x4000, v91
	v_lshlrev_b64 v[2:3], 11, v[96:97]
	v_lshl_add_u64 v[4:5], v[68:69], 0, v[0:1]
	s_mov_b32 m0, s6
	v_readfirstlane_b32 s6, v8
	v_add_u32_e32 v10, 0x1000, v91
	v_lshl_add_u64 v[6:7], v[70:71], 0, v[2:3]
	global_load_lds_dwordx4 v[4:5], off
	s_mov_b32 m0, s6
	s_mov_b64 s[58:59], 0x10000
	v_readfirstlane_b32 s6, v10
	v_add_u32_e32 v10, 0x5000, v91
	global_load_lds_dwordx4 v[6:7], off
	v_lshl_add_u64 v[8:9], v[4:5], 0, s[58:59]
	s_mov_b32 m0, s6
	v_readfirstlane_b32 s6, v10
	v_add_u32_e32 v10, 0x2000, v91
	global_load_lds_dwordx4 v[8:9], off
	v_lshl_add_u64 v[8:9], v[6:7], 0, s[58:59]
	s_mov_b32 m0, s6
	s_mov_b64 s[58:59], 0x20000
	v_readfirstlane_b32 s6, v10
	v_add_u32_e32 v10, 0x6000, v91
	global_load_lds_dwordx4 v[8:9], off
	v_lshl_add_u64 v[8:9], v[4:5], 0, s[58:59]
	s_mov_b32 m0, s6
	v_readfirstlane_b32 s6, v10
	global_load_lds_dwordx4 v[8:9], off
	v_lshl_add_u64 v[8:9], v[6:7], 0, s[58:59]
	s_mov_b32 m0, s6
	s_mov_b64 s[58:59], 0x30000
	global_load_lds_dwordx4 v[8:9], off
	v_add_u32_e32 v8, 0x3000, v91
	v_lshl_add_u64 v[4:5], v[4:5], 0, s[58:59]
	v_readfirstlane_b32 s6, v8
	s_mov_b32 m0, s6
	v_lshl_add_u64 v[74:75], v[72:73], 0, v[0:1]
	global_load_lds_dwordx4 v[4:5], off
	v_lshl_add_u64 v[4:5], v[6:7], 0, s[58:59]
	v_add_u32_e32 v6, 0x7000, v91
	v_mov_b32_e32 v0, 0
	v_readfirstlane_b32 s6, v6
	s_mov_b32 m0, s6
	s_mov_b64 s[52:53], s[92:93]
	global_load_lds_dwordx4 v[4:5], off
	s_nop 0
	v_lshl_add_u64 v[76:77], v[72:73], 0, v[2:3]
	s_mov_b32 s58, 0
	s_mov_b64 s[6:7], 0
	v_mov_b32_e32 v1, v0
	v_mov_b32_e32 v2, v0
	v_mov_b32_e32 v3, v0
	v_mov_b32_e32 v4, v0
	v_mov_b32_e32 v5, v0
	v_mov_b32_e32 v6, v0
	v_mov_b32_e32 v7, v0
	v_mov_b32_e32 v8, v0
	v_mov_b32_e32 v9, v0
	v_mov_b32_e32 v10, v0
	v_mov_b32_e32 v11, v0
	v_mov_b32_e32 v12, v0
	v_mov_b32_e32 v13, v0
	v_mov_b32_e32 v14, v0
	v_mov_b32_e32 v15, v0
	v_mov_b32_e32 v16, v0
	v_mov_b32_e32 v17, v0
	v_mov_b32_e32 v18, v0
	v_mov_b32_e32 v19, v0
	v_mov_b32_e32 v20, v0
	v_mov_b32_e32 v21, v0
	v_mov_b32_e32 v22, v0
	v_mov_b32_e32 v23, v0
	v_mov_b32_e32 v24, v0
	v_mov_b32_e32 v25, v0
	v_mov_b32_e32 v26, v0
	v_mov_b32_e32 v27, v0
	v_mov_b32_e32 v28, v0
	v_mov_b32_e32 v29, v0
	v_mov_b32_e32 v30, v0
	v_mov_b32_e32 v31, v0
	v_mov_b32_e32 v32, v0
	v_mov_b32_e32 v33, v0
	v_mov_b32_e32 v34, v0
	v_mov_b32_e32 v35, v0
	v_mov_b32_e32 v36, v0
	v_mov_b32_e32 v37, v0
	v_mov_b32_e32 v38, v0
	v_mov_b32_e32 v39, v0
	v_mov_b32_e32 v40, v0
	v_mov_b32_e32 v41, v0
	v_mov_b32_e32 v42, v0
	v_mov_b32_e32 v43, v0
	v_mov_b32_e32 v44, v0
	v_mov_b32_e32 v45, v0
	v_mov_b32_e32 v46, v0
	v_mov_b32_e32 v47, v0
	v_mov_b32_e32 v48, v0
	v_mov_b32_e32 v49, v0
	v_mov_b32_e32 v50, v0
	v_mov_b32_e32 v51, v0
	v_mov_b32_e32 v52, v0
	v_mov_b32_e32 v53, v0
	v_mov_b32_e32 v54, v0
	v_mov_b32_e32 v55, v0
	v_mov_b32_e32 v56, v0
	v_mov_b32_e32 v57, v0
	v_mov_b32_e32 v58, v0
	v_mov_b32_e32 v59, v0
	v_mov_b32_e32 v60, v0
	v_mov_b32_e32 v61, v0
	v_mov_b32_e32 v62, v0
	v_mov_b32_e32 v63, v0
	s_mov_b64 s[88:89], 0x4101080
	s_mov_b64 s[90:91], 0x4111080
	s_mov_b64 s[94:95], 0x4121080
	s_mov_b64 vcc, 0x4131080
	s_mov_b64 s[92:93], 0x13931080
	s_mov_b64 s[38:39], 0x13941080
	s_mov_b64 s[62:63], 0x13951080
	s_mov_b64 s[68:69], 0x13961080
	s_add_i32 s59, s58, 0x8000
	s_and_b32 s60, s59, 0x8000
	v_add_u32_e32 v79, s60, v91
	v_lshl_add_u64 v[80:81], v[74:75], 0, s[6:7]
	v_add_u32_e32 v88, 0x4000, v79
	v_readfirstlane_b32 s60, v79
	v_lshl_add_u64 v[82:83], v[80:81], 0, s[88:89]
	v_lshl_add_u64 v[84:85], v[76:77], 0, s[6:7]
	s_mov_b32 m0, s60
	v_readfirstlane_b32 s60, v88
	v_lshl_add_u64 v[86:87], v[84:85], 0, s[92:93]
	global_load_lds_dwordx4 v[82:83], off
	s_mov_b32 m0, s60
	v_lshl_add_u64 v[82:83], v[80:81], 0, s[90:91]
	global_load_lds_dwordx4 v[86:87], off
	v_add_u32_e32 v86, 0x1000, v79
	s_nop 0
	v_readfirstlane_b32 s60, v86
	v_add_u32_e32 v86, 0x5000, v79
	s_mov_b32 m0, s60
	v_readfirstlane_b32 s60, v86
	v_add_u32_e32 v86, 0x2000, v79
	global_load_lds_dwordx4 v[82:83], off
	v_lshl_add_u64 v[82:83], v[84:85], 0, s[38:39]
	s_mov_b32 m0, s60
	v_readfirstlane_b32 s60, v86
	v_add_u32_e32 v86, 0x6000, v79
	global_load_lds_dwordx4 v[82:83], off
	v_lshl_add_u64 v[82:83], v[80:81], 0, s[94:95]
	s_mov_b32 m0, s60
	v_readfirstlane_b32 s60, v86
	global_load_lds_dwordx4 v[82:83], off
	v_lshl_add_u64 v[82:83], v[84:85], 0, s[62:63]
	s_mov_b32 m0, s60
	v_lshl_add_u64 v[80:81], v[80:81], 0, vcc
	global_load_lds_dwordx4 v[82:83], off
	v_add_u32_e32 v82, 0x3000, v79
	v_add_u32_e32 v79, 0x7000, v79
	v_readfirstlane_b32 s60, v82
	s_mov_b32 m0, s60
	v_readfirstlane_b32 s60, v79
	global_load_lds_dwordx4 v[80:81], off
	v_lshl_add_u64 v[80:81], v[84:85], 0, s[68:69]
	s_mov_b32 m0, s60
	s_nop 0
	global_load_lds_dwordx4 v[80:81], off
	s_waitcnt vmcnt(8) lgkmcnt(0)
	s_barrier
.LBB0_214:
	s_add_i32 s59, s58, 0x8000
	s_and_b32 s58, s58, 0x8000
	s_add_i32 s58, s58, 0
	v_add_u32_e32 v79, s58, v95
	v_add_u32_e32 v88, v79, v100
	v_add_u32_e32 v79, v79, v93
	ds_read_b128 v[80:83], v88
	ds_read_b128 v[84:87], v88 offset:2048
	ds_read_b128 v[110:113], v88 offset:4096
	ds_read_b128 v[114:117], v88 offset:6144
	ds_read_b128 v[118:121], v79 offset:16384
	ds_read_b128 v[122:125], v79 offset:18432
	ds_read_b128 v[126:129], v79 offset:20480
	ds_read_b128 v[130:133], v79 offset:22528
	v_add_u32_e32 v206, s58, v101
	v_add_u32_e32 v207, v206, v100
	v_add_u32_e32 v208, v206, v93
	ds_read_b128 v[210:213], v207
	ds_read_b128 v[214:217], v207 offset:2048
	ds_read_b128 v[218:221], v207 offset:4096
	ds_read_b128 v[222:225], v207 offset:6144
	ds_read_b128 v[226:229], v208 offset:16384
	ds_read_b128 v[230:233], v208 offset:18432
	ds_read_b128 v[234:237], v208 offset:20480
	ds_read_b128 v[238:241], v208 offset:22528
	s_setprio 1
	s_waitcnt lgkmcnt(8)
	v_mfma_f32_16x16x32_bf16 v[60:63], v[118:121], v[80:83], v[60:63]
	v_mfma_f32_16x16x32_bf16 v[56:59], v[122:125], v[80:83], v[56:59]
	v_mfma_f32_16x16x32_bf16 v[52:55], v[126:129], v[80:83], v[52:55]
	v_mfma_f32_16x16x32_bf16 v[48:51], v[130:133], v[80:83], v[48:51]
	v_mfma_f32_16x16x32_bf16 v[44:47], v[118:121], v[84:87], v[44:47]
	v_mfma_f32_16x16x32_bf16 v[40:43], v[122:125], v[84:87], v[40:43]
	v_mfma_f32_16x16x32_bf16 v[36:39], v[126:129], v[84:87], v[36:39]
	v_mfma_f32_16x16x32_bf16 v[32:35], v[130:133], v[84:87], v[32:35]
	v_mfma_f32_16x16x32_bf16 v[28:31], v[118:121], v[110:113], v[28:31]
	v_mfma_f32_16x16x32_bf16 v[24:27], v[122:125], v[110:113], v[24:27]
	v_mfma_f32_16x16x32_bf16 v[20:23], v[126:129], v[110:113], v[20:23]
	v_mfma_f32_16x16x32_bf16 v[16:19], v[130:133], v[110:113], v[16:19]
	v_mfma_f32_16x16x32_bf16 v[12:15], v[118:121], v[114:117], v[12:15]
	v_mfma_f32_16x16x32_bf16 v[8:11], v[122:125], v[114:117], v[8:11]
	v_mfma_f32_16x16x32_bf16 v[4:7], v[126:129], v[114:117], v[4:7]
	v_mfma_f32_16x16x32_bf16 v[0:3], v[130:133], v[114:117], v[0:3]
	s_setprio 0
	s_setprio 1
	s_waitcnt lgkmcnt(0)
	s_setprio 0
	s_barrier
	s_add_u32 s6, s6, 0x80
	s_addc_u32 s7, s7, 0
	s_mov_b32 s60, s58
	v_add_u32_e32 v79, s60, v91
	v_lshl_add_u64 v[80:81], v[74:75], 0, s[6:7]
	v_add_u32_e32 v88, 0x4000, v79
	v_readfirstlane_b32 s60, v79
	v_lshl_add_u64 v[82:83], v[80:81], 0, s[88:89]
	v_lshl_add_u64 v[84:85], v[76:77], 0, s[6:7]
	s_mov_b32 m0, s60
	v_readfirstlane_b32 s60, v88
	v_lshl_add_u64 v[86:87], v[84:85], 0, s[92:93]
	global_load_lds_dwordx4 v[82:83], off
	s_mov_b32 m0, s60
	v_lshl_add_u64 v[82:83], v[80:81], 0, s[90:91]
	global_load_lds_dwordx4 v[86:87], off
	v_add_u32_e32 v86, 0x1000, v79
	s_nop 0
	v_readfirstlane_b32 s60, v86
	v_add_u32_e32 v86, 0x5000, v79
	s_mov_b32 m0, s60
	v_readfirstlane_b32 s60, v86
	v_add_u32_e32 v86, 0x2000, v79
	global_load_lds_dwordx4 v[82:83], off
	v_lshl_add_u64 v[82:83], v[84:85], 0, s[38:39]
	s_mov_b32 m0, s60
	v_readfirstlane_b32 s60, v86
	v_add_u32_e32 v86, 0x6000, v79
	global_load_lds_dwordx4 v[82:83], off
	v_lshl_add_u64 v[82:83], v[80:81], 0, s[94:95]
	s_mov_b32 m0, s60
	v_readfirstlane_b32 s60, v86
	global_load_lds_dwordx4 v[82:83], off
	v_lshl_add_u64 v[82:83], v[84:85], 0, s[62:63]
	s_mov_b32 m0, s60
	v_lshl_add_u64 v[80:81], v[80:81], 0, vcc
	global_load_lds_dwordx4 v[82:83], off
	v_add_u32_e32 v82, 0x3000, v79
	v_add_u32_e32 v79, 0x7000, v79
	v_readfirstlane_b32 s60, v82
	s_mov_b32 m0, s60
	v_readfirstlane_b32 s60, v79
	global_load_lds_dwordx4 v[80:81], off
	v_lshl_add_u64 v[80:81], v[84:85], 0, s[68:69]
	s_mov_b32 m0, s60
	s_nop 0
	global_load_lds_dwordx4 v[80:81], off
	s_setprio 1
	v_mfma_f32_16x16x32_bf16 v[60:63], v[226:229], v[210:213], v[60:63]
	v_mfma_f32_16x16x32_bf16 v[56:59], v[230:233], v[210:213], v[56:59]
	v_mfma_f32_16x16x32_bf16 v[52:55], v[234:237], v[210:213], v[52:55]
	v_mfma_f32_16x16x32_bf16 v[48:51], v[238:241], v[210:213], v[48:51]
	v_mfma_f32_16x16x32_bf16 v[44:47], v[226:229], v[214:217], v[44:47]
	v_mfma_f32_16x16x32_bf16 v[40:43], v[230:233], v[214:217], v[40:43]
	v_mfma_f32_16x16x32_bf16 v[36:39], v[234:237], v[214:217], v[36:39]
	v_mfma_f32_16x16x32_bf16 v[32:35], v[238:241], v[214:217], v[32:35]
	v_mfma_f32_16x16x32_bf16 v[28:31], v[226:229], v[218:221], v[28:31]
	v_mfma_f32_16x16x32_bf16 v[24:27], v[230:233], v[218:221], v[24:27]
	v_mfma_f32_16x16x32_bf16 v[20:23], v[234:237], v[218:221], v[20:23]
	v_mfma_f32_16x16x32_bf16 v[16:19], v[238:241], v[218:221], v[16:19]
	v_mfma_f32_16x16x32_bf16 v[12:15], v[226:229], v[222:225], v[12:15]
	v_mfma_f32_16x16x32_bf16 v[8:11], v[230:233], v[222:225], v[8:11]
	v_mfma_f32_16x16x32_bf16 v[4:7], v[234:237], v[222:225], v[4:7]
	v_mfma_f32_16x16x32_bf16 v[0:3], v[238:241], v[222:225], v[0:3]
	s_setprio 0
	s_cmpk_lg_i32 s6, 0x700
	s_mov_b32 s58, s59
	s_waitcnt vmcnt(8)
	s_barrier
	s_cbranch_scc1 .LBB0_214
	s_add_i32 s59, s58, 0x8000
	s_and_b32 s58, s58, 0x8000
	s_add_i32 s58, s58, 0
	v_add_u32_e32 v79, s58, v95
	v_add_u32_e32 v88, v79, v100
	v_add_u32_e32 v79, v79, v93
	ds_read_b128 v[80:83], v88
	ds_read_b128 v[84:87], v88 offset:2048
	ds_read_b128 v[110:113], v88 offset:4096
	ds_read_b128 v[114:117], v88 offset:6144
	ds_read_b128 v[118:121], v79 offset:16384
	ds_read_b128 v[122:125], v79 offset:18432
	ds_read_b128 v[126:129], v79 offset:20480
	ds_read_b128 v[130:133], v79 offset:22528
	v_add_u32_e32 v206, s58, v101
	v_add_u32_e32 v207, v206, v100
	v_add_u32_e32 v208, v206, v93
	ds_read_b128 v[210:213], v207
	ds_read_b128 v[214:217], v207 offset:2048
	ds_read_b128 v[218:221], v207 offset:4096
	ds_read_b128 v[222:225], v207 offset:6144
	ds_read_b128 v[226:229], v208 offset:16384
	ds_read_b128 v[230:233], v208 offset:18432
	ds_read_b128 v[234:237], v208 offset:20480
	ds_read_b128 v[238:241], v208 offset:22528
	s_setprio 1
	s_waitcnt lgkmcnt(8)
	v_mfma_f32_16x16x32_bf16 v[60:63], v[118:121], v[80:83], v[60:63]
	v_mfma_f32_16x16x32_bf16 v[56:59], v[122:125], v[80:83], v[56:59]
	v_mfma_f32_16x16x32_bf16 v[52:55], v[126:129], v[80:83], v[52:55]
	v_mfma_f32_16x16x32_bf16 v[48:51], v[130:133], v[80:83], v[48:51]
	v_mfma_f32_16x16x32_bf16 v[44:47], v[118:121], v[84:87], v[44:47]
	v_mfma_f32_16x16x32_bf16 v[40:43], v[122:125], v[84:87], v[40:43]
	v_mfma_f32_16x16x32_bf16 v[36:39], v[126:129], v[84:87], v[36:39]
	v_mfma_f32_16x16x32_bf16 v[32:35], v[130:133], v[84:87], v[32:35]
	v_mfma_f32_16x16x32_bf16 v[28:31], v[118:121], v[110:113], v[28:31]
	v_mfma_f32_16x16x32_bf16 v[24:27], v[122:125], v[110:113], v[24:27]
	v_mfma_f32_16x16x32_bf16 v[20:23], v[126:129], v[110:113], v[20:23]
	v_mfma_f32_16x16x32_bf16 v[16:19], v[130:133], v[110:113], v[16:19]
	v_mfma_f32_16x16x32_bf16 v[12:15], v[118:121], v[114:117], v[12:15]
	v_mfma_f32_16x16x32_bf16 v[8:11], v[122:125], v[114:117], v[8:11]
	v_mfma_f32_16x16x32_bf16 v[4:7], v[126:129], v[114:117], v[4:7]
	v_mfma_f32_16x16x32_bf16 v[0:3], v[130:133], v[114:117], v[0:3]
	s_setprio 0
	s_setprio 1
	s_waitcnt lgkmcnt(0)
	v_mfma_f32_16x16x32_bf16 v[60:63], v[226:229], v[210:213], v[60:63]
	v_mfma_f32_16x16x32_bf16 v[56:59], v[230:233], v[210:213], v[56:59]
	v_mfma_f32_16x16x32_bf16 v[52:55], v[234:237], v[210:213], v[52:55]
	v_mfma_f32_16x16x32_bf16 v[48:51], v[238:241], v[210:213], v[48:51]
	v_mfma_f32_16x16x32_bf16 v[44:47], v[226:229], v[214:217], v[44:47]
	v_mfma_f32_16x16x32_bf16 v[40:43], v[230:233], v[214:217], v[40:43]
	v_mfma_f32_16x16x32_bf16 v[36:39], v[234:237], v[214:217], v[36:39]
	v_mfma_f32_16x16x32_bf16 v[32:35], v[238:241], v[214:217], v[32:35]
	v_mfma_f32_16x16x32_bf16 v[28:31], v[226:229], v[218:221], v[28:31]
	v_mfma_f32_16x16x32_bf16 v[24:27], v[230:233], v[218:221], v[24:27]
	v_mfma_f32_16x16x32_bf16 v[20:23], v[234:237], v[218:221], v[20:23]
	v_mfma_f32_16x16x32_bf16 v[16:19], v[238:241], v[218:221], v[16:19]
	v_mfma_f32_16x16x32_bf16 v[12:15], v[226:229], v[222:225], v[12:15]
	v_mfma_f32_16x16x32_bf16 v[8:11], v[230:233], v[222:225], v[8:11]
	v_mfma_f32_16x16x32_bf16 v[4:7], v[234:237], v[222:225], v[4:7]
	v_mfma_f32_16x16x32_bf16 v[0:3], v[238:241], v[222:225], v[0:3]
	s_setprio 0
	s_mov_b32 s58, s59
	s_waitcnt vmcnt(0)
	s_barrier
	v_add_u32_e32 v79, v104, v93
	ds_read_b128 v[74:77], v79 offset:55296
	ds_read_b128 v[80:83], v79 offset:53248
	ds_read_b128 v[84:87], v79 offset:51200
	ds_read_b128 v[110:113], v79 offset:49152
	v_add_u32_e32 v79, v104, v100
	ds_read_b128 v[114:117], v79 offset:38912
	ds_read_b128 v[118:121], v79 offset:36864
	ds_read_b128 v[122:125], v79 offset:34816
	ds_read_b128 v[126:129], v79 offset:32768
	s_setprio 1
	s_waitcnt lgkmcnt(0)
	v_mfma_f32_16x16x32_bf16 v[60:63], v[110:113], v[126:129], v[60:63]
	v_mfma_f32_16x16x32_bf16 v[56:59], v[84:87], v[126:129], v[56:59]
	v_mfma_f32_16x16x32_bf16 v[52:55], v[80:83], v[126:129], v[52:55]
	v_mfma_f32_16x16x32_bf16 v[48:51], v[74:77], v[126:129], v[48:51]
	v_mfma_f32_16x16x32_bf16 v[44:47], v[110:113], v[122:125], v[44:47]
	v_mfma_f32_16x16x32_bf16 v[40:43], v[84:87], v[122:125], v[40:43]
	v_mfma_f32_16x16x32_bf16 v[36:39], v[80:83], v[122:125], v[36:39]
	v_mfma_f32_16x16x32_bf16 v[32:35], v[74:77], v[122:125], v[32:35]
	v_mfma_f32_16x16x32_bf16 v[28:31], v[110:113], v[118:121], v[28:31]
	v_mfma_f32_16x16x32_bf16 v[24:27], v[84:87], v[118:121], v[24:27]
	v_mfma_f32_16x16x32_bf16 v[20:23], v[80:83], v[118:121], v[20:23]
	v_mfma_f32_16x16x32_bf16 v[16:19], v[74:77], v[118:121], v[16:19]
	v_mfma_f32_16x16x32_bf16 v[12:15], v[110:113], v[114:117], v[12:15]
	v_mfma_f32_16x16x32_bf16 v[8:11], v[84:87], v[114:117], v[8:11]
	v_mfma_f32_16x16x32_bf16 v[4:7], v[80:83], v[114:117], v[4:7]
	v_mfma_f32_16x16x32_bf16 v[0:3], v[74:77], v[114:117], v[0:3]
	s_setprio 0
	v_add_u32_e32 v79, v105, v100
	ds_read_b128 v[74:77], v79 offset:32768
	ds_read_b128 v[80:83], v79 offset:34816
	ds_read_b128 v[84:87], v79 offset:36864
	ds_read_b128 v[110:113], v79 offset:38912
	v_add_u32_e32 v79, v105, v93
	ds_read_b128 v[114:117], v79 offset:49152
	ds_read_b128 v[118:121], v79 offset:51200
	ds_read_b128 v[122:125], v79 offset:53248
	ds_read_b128 v[126:129], v79 offset:55296
	s_setprio 1
	s_waitcnt lgkmcnt(3)
	v_mfma_f32_16x16x32_bf16 v[60:63], v[114:117], v[74:77], v[60:63]
	s_waitcnt lgkmcnt(2)
	v_mfma_f32_16x16x32_bf16 v[56:59], v[118:121], v[74:77], v[56:59]
	s_waitcnt lgkmcnt(1)
	v_mfma_f32_16x16x32_bf16 v[52:55], v[122:125], v[74:77], v[52:55]
	s_waitcnt lgkmcnt(0)
	v_mfma_f32_16x16x32_bf16 v[48:51], v[126:129], v[74:77], v[48:51]
	v_mfma_f32_16x16x32_bf16 v[44:47], v[114:117], v[80:83], v[44:47]
	v_mfma_f32_16x16x32_bf16 v[40:43], v[118:121], v[80:83], v[40:43]
	v_mfma_f32_16x16x32_bf16 v[36:39], v[122:125], v[80:83], v[36:39]
	v_mfma_f32_16x16x32_bf16 v[32:35], v[126:129], v[80:83], v[32:35]
	v_mfma_f32_16x16x32_bf16 v[28:31], v[114:117], v[84:87], v[28:31]
	v_mfma_f32_16x16x32_bf16 v[24:27], v[118:121], v[84:87], v[24:27]
	v_mfma_f32_16x16x32_bf16 v[20:23], v[122:125], v[84:87], v[20:23]
	v_mfma_f32_16x16x32_bf16 v[16:19], v[126:129], v[84:87], v[16:19]
	v_mfma_f32_16x16x32_bf16 v[12:15], v[114:117], v[110:113], v[12:15]
	v_mfma_f32_16x16x32_bf16 v[8:11], v[118:121], v[110:113], v[8:11]
	v_mfma_f32_16x16x32_bf16 v[4:7], v[122:125], v[110:113], v[4:7]
	v_mfma_f32_16x16x32_bf16 v[0:3], v[126:129], v[110:113], v[0:3]
	s_setprio 0
	s_waitcnt vmcnt(0)
	v_and_b32_e32 v74, 0xfffff8, v78
	v_cmp_ne_u32_e32 vcc, 16, v74
	s_mov_b64 s[6:7], s[0:1]
	s_barrier
	s_and_saveexec_b64 s[58:59], vcc
	s_mov_b64 s[92:93], s[52:53]
	s_cbranch_execz .LBB0_160
	v_readlane_b32 s6, v254, 29
	v_readlane_b32 s7, v254, 30
	v_cmp_lt_u32_e32 vcc, 23, v78
	v_lshlrev_b32_e32 v80, 7, v67
	v_lshl_add_u64 v[74:75], v[96:97], 1, s[6:7]
	v_mul_f32_e32 v83, 0xbfb8aa3b, v60
	v_mul_f32_e32 v84, 0xbfb8aa3b, v61
	v_mul_f32_e32 v79, 0xbfb8aa3b, v62
	v_mul_f32_e32 v82, 0xbfb8aa3b, v63
	v_mul_f32_e32 v126, 0xbfb8aa3b, v56
	v_mul_f32_e32 v127, 0xbfb8aa3b, v57
	v_mul_f32_e32 v124, 0xbfb8aa3b, v58
	v_mul_f32_e32 v125, 0xbfb8aa3b, v59
	v_mul_f32_e32 v122, 0xbfb8aa3b, v52
	v_mul_f32_e32 v123, 0xbfb8aa3b, v53
	v_mul_f32_e32 v120, 0xbfb8aa3b, v54
	v_mul_f32_e32 v121, 0xbfb8aa3b, v55
	v_mul_f32_e32 v118, 0xbfb8aa3b, v48
	v_mul_f32_e32 v119, 0xbfb8aa3b, v49
	v_mul_f32_e32 v116, 0xbfb8aa3b, v50
	v_mul_f32_e32 v117, 0xbfb8aa3b, v51
	v_mul_f32_e32 v114, 0xbfb8aa3b, v44
	v_mul_f32_e32 v115, 0xbfb8aa3b, v45
	v_mul_f32_e32 v112, 0xbfb8aa3b, v46
	v_mul_f32_e32 v113, 0xbfb8aa3b, v47
	v_mul_f32_e32 v110, 0xbfb8aa3b, v40
	v_mul_f32_e32 v111, 0xbfb8aa3b, v41
	v_mul_f32_e32 v67, 0xbfb8aa3b, v42
	v_mul_f32_e32 v109, 0xbfb8aa3b, v43
	s_and_saveexec_b64 s[6:7], vcc
	s_xor_b64 s[60:61], exec, s[6:7]
	s_cbranch_execz .LBB0_218
	v_mov_b32_e32 v40, v97
	s_nop 0
	v_add_u32_e32 v40, v40, v176
	v_ashrrev_i32_e32 v42, 1, v40
	v_and_b32_e32 v41, 64, v40
	v_and_b32_e32 v42, 0xffffffc0, v42
	v_lshrrev_b32_e32 v43, 2, v40
	v_and_or_b32 v40, v40, 15, v80
	v_and_or_b32 v43, v43, 12, v41
	v_add_u32_e32 v42, v40, v42
	v_exp_f32_e32 v44, v83
	v_exp_f32_e32 v45, v79
	v_lshlrev_b32_e32 v96, 1, v43
	v_exp_f32_e32 v46, v84
	v_exp_f32_e32 v47, v82
	v_pk_add_f32 v[44:45], v[44:45], 1.0 op_sel_hi:[1,0]
	s_movk_i32 s67, 0x3200
	v_div_scale_f32 v43, s[6:7], v44, v44, 1.0
	v_rcp_f32_e32 v48, v43
	v_mad_i64_i32 v[40:41], s[6:7], v42, s67, v[74:75]
	v_lshl_add_u64 v[40:41], v[40:41], 0, v[96:97]
	v_fma_f32 v49, -v43, v48, 1.0
	v_fmac_f32_e32 v48, v49, v48
	v_div_scale_f32 v49, vcc, 1.0, v44, 1.0
	v_mul_f32_e32 v50, v49, v48
	v_fma_f32 v51, -v43, v50, v49
	v_fmac_f32_e32 v50, v51, v48
	v_fma_f32 v43, -v43, v50, v49
	v_div_fmas_f32 v43, v43, v48, v50
	v_div_fixup_f32 v43, v43, v44, 1.0
	v_div_scale_f32 v44, s[6:7], v45, v45, 1.0
	v_rcp_f32_e32 v48, v44
	s_nop 0
	v_fma_f32 v49, -v44, v48, 1.0
	v_fmac_f32_e32 v48, v49, v48
	v_div_scale_f32 v49, vcc, 1.0, v45, 1.0
	v_mul_f32_e32 v50, v49, v48
	v_fma_f32 v51, -v44, v50, v49
	v_fmac_f32_e32 v50, v51, v48
	v_fma_f32 v44, -v44, v50, v49
	v_div_fmas_f32 v44, v44, v48, v50
	v_div_fixup_f32 v48, v44, v45, 1.0
	v_pk_add_f32 v[44:45], v[46:47], 1.0 op_sel_hi:[1,0]
	s_nop 0
	v_div_scale_f32 v46, s[6:7], v44, v44, 1.0
	v_rcp_f32_e32 v47, v46
	s_nop 0
	v_fma_f32 v49, -v46, v47, 1.0
	v_fmac_f32_e32 v47, v49, v47
	v_div_scale_f32 v49, vcc, 1.0, v44, 1.0
	v_mul_f32_e32 v50, v49, v47
	v_fma_f32 v51, -v46, v50, v49
	v_fmac_f32_e32 v50, v51, v47
	v_fma_f32 v46, -v46, v50, v49
	v_div_fmas_f32 v46, v46, v47, v50
	v_div_fixup_f32 v44, v46, v44, 1.0
	v_div_scale_f32 v46, s[6:7], v45, v45, 1.0
	v_rcp_f32_e32 v47, v46
	s_nop 0
	v_fma_f32 v49, -v46, v47, 1.0
	v_fmac_f32_e32 v47, v49, v47
	v_div_scale_f32 v49, vcc, 1.0, v45, 1.0
	v_mul_f32_e32 v50, v49, v47
	v_fma_f32 v51, -v46, v50, v49
	v_fmac_f32_e32 v50, v51, v47
	v_fma_f32 v46, -v46, v50, v49
	v_div_fmas_f32 v46, v46, v47, v50
	v_div_fixup_f32 v45, v46, v45, 1.0
	v_and_b32_sdwa v46, v48, v154 dst_sel:DWORD dst_unused:UNUSED_PAD src0_sel:WORD_1 src1_sel:DWORD
	v_and_b32_sdwa v47, v43, v154 dst_sel:DWORD dst_unused:UNUSED_PAD src0_sel:WORD_1 src1_sel:DWORD
	v_add3_u32 v43, v43, v47, s33
	v_add3_u32 v46, v48, v46, s33
	v_and_b32_sdwa v47, v45, v154 dst_sel:DWORD dst_unused:UNUSED_PAD src0_sel:WORD_1 src1_sel:DWORD
	v_and_b32_sdwa v48, v44, v154 dst_sel:DWORD dst_unused:UNUSED_PAD src0_sel:WORD_1 src1_sel:DWORD
	v_add3_u32 v45, v45, v47, s33
	v_add3_u32 v44, v44, v48, s33
	v_and_b32_e32 v45, 0xffff0000, v45
	v_and_b32_e32 v44, 0xffff0000, v44
	v_or_b32_sdwa v45, v45, v46 dst_sel:DWORD dst_unused:UNUSED_PAD src0_sel:DWORD src1_sel:WORD_1
	v_or_b32_sdwa v44, v44, v43 dst_sel:DWORD dst_unused:UNUSED_PAD src0_sel:DWORD src1_sel:WORD_1
	global_store_dwordx2 v[40:41], v[44:45], off
	v_exp_f32_e32 v44, v126
	v_exp_f32_e32 v45, v124
	v_exp_f32_e32 v46, v127
	v_exp_f32_e32 v47, v125
	v_pk_add_f32 v[44:45], v[44:45], 1.0 op_sel_hi:[1,0]
	s_nop 0
	v_div_scale_f32 v43, s[6:7], v44, v44, 1.0
	v_rcp_f32_e32 v48, v43
	s_nop 0
	v_fma_f32 v49, -v43, v48, 1.0
	v_fmac_f32_e32 v48, v49, v48
	v_div_scale_f32 v49, vcc, 1.0, v44, 1.0
	v_mul_f32_e32 v50, v49, v48
	v_fma_f32 v51, -v43, v50, v49
	v_fmac_f32_e32 v50, v51, v48
	v_fma_f32 v43, -v43, v50, v49
	v_div_fmas_f32 v43, v43, v48, v50
	v_div_fixup_f32 v43, v43, v44, 1.0
	v_div_scale_f32 v44, s[6:7], v45, v45, 1.0
	v_rcp_f32_e32 v48, v44
	s_nop 0
	v_fma_f32 v49, -v44, v48, 1.0
	v_fmac_f32_e32 v48, v49, v48
	v_div_scale_f32 v49, vcc, 1.0, v45, 1.0
	v_mul_f32_e32 v50, v49, v48
	v_fma_f32 v51, -v44, v50, v49
	v_fmac_f32_e32 v50, v51, v48
	v_fma_f32 v44, -v44, v50, v49
	v_div_fmas_f32 v44, v44, v48, v50
	v_div_fixup_f32 v48, v44, v45, 1.0
	v_pk_add_f32 v[44:45], v[46:47], 1.0 op_sel_hi:[1,0]
	s_nop 0
	v_div_scale_f32 v46, s[6:7], v44, v44, 1.0
	v_rcp_f32_e32 v47, v46
	s_nop 0
	v_fma_f32 v49, -v46, v47, 1.0
	v_fmac_f32_e32 v47, v49, v47
	v_div_scale_f32 v49, vcc, 1.0, v44, 1.0
	v_mul_f32_e32 v50, v49, v47
	v_fma_f32 v51, -v46, v50, v49
	v_fmac_f32_e32 v50, v51, v47
	v_fma_f32 v46, -v46, v50, v49
	v_div_fmas_f32 v46, v46, v47, v50
	v_div_fixup_f32 v44, v46, v44, 1.0
	v_div_scale_f32 v46, s[6:7], v45, v45, 1.0
	v_rcp_f32_e32 v47, v46
	s_nop 0
	v_fma_f32 v49, -v46, v47, 1.0
	v_fmac_f32_e32 v47, v49, v47
	v_div_scale_f32 v49, vcc, 1.0, v45, 1.0
	v_mul_f32_e32 v50, v49, v47
	v_fma_f32 v51, -v46, v50, v49
	v_fmac_f32_e32 v50, v51, v47
	v_fma_f32 v46, -v46, v50, v49
	v_div_fmas_f32 v46, v46, v47, v50
	v_div_fixup_f32 v45, v46, v45, 1.0
	v_and_b32_sdwa v46, v48, v154 dst_sel:DWORD dst_unused:UNUSED_PAD src0_sel:WORD_1 src1_sel:DWORD
	v_and_b32_sdwa v47, v43, v154 dst_sel:DWORD dst_unused:UNUSED_PAD src0_sel:WORD_1 src1_sel:DWORD
	v_add3_u32 v43, v43, v47, s33
	v_add3_u32 v46, v48, v46, s33
	v_and_b32_sdwa v47, v45, v154 dst_sel:DWORD dst_unused:UNUSED_PAD src0_sel:WORD_1 src1_sel:DWORD
	v_and_b32_sdwa v48, v44, v154 dst_sel:DWORD dst_unused:UNUSED_PAD src0_sel:WORD_1 src1_sel:DWORD
	v_add3_u32 v45, v45, v47, s33
	v_add3_u32 v44, v44, v48, s33
	v_and_b32_e32 v45, 0xffff0000, v45
	v_and_b32_e32 v44, 0xffff0000, v44
	v_or_b32_sdwa v45, v45, v46 dst_sel:DWORD dst_unused:UNUSED_PAD src0_sel:DWORD src1_sel:WORD_1
	v_or_b32_sdwa v44, v44, v43 dst_sel:DWORD dst_unused:UNUSED_PAD src0_sel:DWORD src1_sel:WORD_1
	global_store_dwordx2 v[40:41], v[44:45], off offset:32
	v_exp_f32_e32 v44, v122
	v_exp_f32_e32 v45, v120
	v_exp_f32_e32 v46, v123
	v_exp_f32_e32 v47, v121
	v_pk_add_f32 v[44:45], v[44:45], 1.0 op_sel_hi:[1,0]
	s_nop 0
	v_div_scale_f32 v43, s[6:7], v44, v44, 1.0
	v_rcp_f32_e32 v48, v43
	s_nop 0
	v_fma_f32 v49, -v43, v48, 1.0
	v_fmac_f32_e32 v48, v49, v48
	v_div_scale_f32 v49, vcc, 1.0, v44, 1.0
	v_mul_f32_e32 v50, v49, v48
	v_fma_f32 v51, -v43, v50, v49
	v_fmac_f32_e32 v50, v51, v48
	v_fma_f32 v43, -v43, v50, v49
	v_div_fmas_f32 v43, v43, v48, v50
	v_div_fixup_f32 v43, v43, v44, 1.0
	v_div_scale_f32 v44, s[6:7], v45, v45, 1.0
	v_rcp_f32_e32 v48, v44
	s_nop 0
	v_fma_f32 v49, -v44, v48, 1.0
	v_fmac_f32_e32 v48, v49, v48
	v_div_scale_f32 v49, vcc, 1.0, v45, 1.0
	v_mul_f32_e32 v50, v49, v48
	v_fma_f32 v51, -v44, v50, v49
	v_fmac_f32_e32 v50, v51, v48
	v_fma_f32 v44, -v44, v50, v49
	v_div_fmas_f32 v44, v44, v48, v50
	v_div_fixup_f32 v48, v44, v45, 1.0
	v_pk_add_f32 v[44:45], v[46:47], 1.0 op_sel_hi:[1,0]
	s_nop 0
	v_div_scale_f32 v46, s[6:7], v44, v44, 1.0
	v_rcp_f32_e32 v47, v46
	s_nop 0
	v_fma_f32 v49, -v46, v47, 1.0
	v_fmac_f32_e32 v47, v49, v47
	v_div_scale_f32 v49, vcc, 1.0, v44, 1.0
	v_mul_f32_e32 v50, v49, v47
	v_fma_f32 v51, -v46, v50, v49
	v_fmac_f32_e32 v50, v51, v47
	v_fma_f32 v46, -v46, v50, v49
	v_div_fmas_f32 v46, v46, v47, v50
	v_div_fixup_f32 v44, v46, v44, 1.0
	v_div_scale_f32 v46, s[6:7], v45, v45, 1.0
	v_rcp_f32_e32 v47, v46
	s_nop 0
	v_fma_f32 v49, -v46, v47, 1.0
	v_fmac_f32_e32 v47, v49, v47
	v_div_scale_f32 v49, vcc, 1.0, v45, 1.0
	v_mul_f32_e32 v50, v49, v47
	v_fma_f32 v51, -v46, v50, v49
	v_fmac_f32_e32 v50, v51, v47
	v_fma_f32 v46, -v46, v50, v49
	v_div_fmas_f32 v46, v46, v47, v50
	v_div_fixup_f32 v45, v46, v45, 1.0
	v_and_b32_sdwa v46, v48, v154 dst_sel:DWORD dst_unused:UNUSED_PAD src0_sel:WORD_1 src1_sel:DWORD
	v_and_b32_sdwa v47, v43, v154 dst_sel:DWORD dst_unused:UNUSED_PAD src0_sel:WORD_1 src1_sel:DWORD
	v_add3_u32 v43, v43, v47, s33
	v_add3_u32 v46, v48, v46, s33
	v_and_b32_sdwa v47, v45, v154 dst_sel:DWORD dst_unused:UNUSED_PAD src0_sel:WORD_1 src1_sel:DWORD
	v_and_b32_sdwa v48, v44, v154 dst_sel:DWORD dst_unused:UNUSED_PAD src0_sel:WORD_1 src1_sel:DWORD
	v_add3_u32 v45, v45, v47, s33
	v_add3_u32 v44, v44, v48, s33
	v_and_b32_e32 v45, 0xffff0000, v45
	v_and_b32_e32 v44, 0xffff0000, v44
	v_or_b32_sdwa v45, v45, v46 dst_sel:DWORD dst_unused:UNUSED_PAD src0_sel:DWORD src1_sel:WORD_1
	v_or_b32_sdwa v44, v44, v43 dst_sel:DWORD dst_unused:UNUSED_PAD src0_sel:DWORD src1_sel:WORD_1
	global_store_dwordx2 v[40:41], v[44:45], off offset:64
	v_exp_f32_e32 v44, v118
	v_exp_f32_e32 v45, v116
	v_exp_f32_e32 v46, v119
	v_exp_f32_e32 v47, v117
	v_pk_add_f32 v[44:45], v[44:45], 1.0 op_sel_hi:[1,0]
	s_nop 0
	v_div_scale_f32 v43, s[6:7], v44, v44, 1.0
	v_rcp_f32_e32 v48, v43
	s_nop 0
	v_fma_f32 v49, -v43, v48, 1.0
	v_fmac_f32_e32 v48, v49, v48
	v_div_scale_f32 v49, vcc, 1.0, v44, 1.0
	v_mul_f32_e32 v50, v49, v48
	v_fma_f32 v51, -v43, v50, v49
	v_fmac_f32_e32 v50, v51, v48
	v_fma_f32 v43, -v43, v50, v49
	v_div_fmas_f32 v43, v43, v48, v50
	v_div_fixup_f32 v43, v43, v44, 1.0
	v_div_scale_f32 v44, s[6:7], v45, v45, 1.0
	v_rcp_f32_e32 v48, v44
	s_nop 0
	v_fma_f32 v49, -v44, v48, 1.0
	v_fmac_f32_e32 v48, v49, v48
	v_div_scale_f32 v49, vcc, 1.0, v45, 1.0
	v_mul_f32_e32 v50, v49, v48
	v_fma_f32 v51, -v44, v50, v49
	v_fmac_f32_e32 v50, v51, v48
	v_fma_f32 v44, -v44, v50, v49
	v_div_fmas_f32 v44, v44, v48, v50
	v_div_fixup_f32 v48, v44, v45, 1.0
	v_pk_add_f32 v[44:45], v[46:47], 1.0 op_sel_hi:[1,0]
	s_nop 0
	v_div_scale_f32 v46, s[6:7], v44, v44, 1.0
	v_rcp_f32_e32 v47, v46
	s_nop 0
	v_fma_f32 v49, -v46, v47, 1.0
	v_fmac_f32_e32 v47, v49, v47
	v_div_scale_f32 v49, vcc, 1.0, v44, 1.0
	v_mul_f32_e32 v50, v49, v47
	v_fma_f32 v51, -v46, v50, v49
	v_fmac_f32_e32 v50, v51, v47
	v_fma_f32 v46, -v46, v50, v49
	v_div_fmas_f32 v46, v46, v47, v50
	v_div_fixup_f32 v44, v46, v44, 1.0
	v_div_scale_f32 v46, s[6:7], v45, v45, 1.0
	v_rcp_f32_e32 v47, v46
	s_nop 0
	v_fma_f32 v49, -v46, v47, 1.0
	v_fmac_f32_e32 v47, v49, v47
	v_div_scale_f32 v49, vcc, 1.0, v45, 1.0
	v_mul_f32_e32 v50, v49, v47
	v_fma_f32 v51, -v46, v50, v49
	v_fmac_f32_e32 v50, v51, v47
	v_fma_f32 v46, -v46, v50, v49
	v_div_fmas_f32 v46, v46, v47, v50
	v_div_fixup_f32 v45, v46, v45, 1.0
	v_and_b32_sdwa v46, v48, v154 dst_sel:DWORD dst_unused:UNUSED_PAD src0_sel:WORD_1 src1_sel:DWORD
	v_and_b32_sdwa v47, v43, v154 dst_sel:DWORD dst_unused:UNUSED_PAD src0_sel:WORD_1 src1_sel:DWORD
	v_add3_u32 v43, v43, v47, s33
	v_add3_u32 v46, v48, v46, s33
	v_and_b32_sdwa v47, v45, v154 dst_sel:DWORD dst_unused:UNUSED_PAD src0_sel:WORD_1 src1_sel:DWORD
	v_and_b32_sdwa v48, v44, v154 dst_sel:DWORD dst_unused:UNUSED_PAD src0_sel:WORD_1 src1_sel:DWORD
	v_add3_u32 v45, v45, v47, s33
	v_add3_u32 v44, v44, v48, s33
	v_and_b32_e32 v45, 0xffff0000, v45
	v_and_b32_e32 v44, 0xffff0000, v44
	v_or_b32_sdwa v45, v45, v46 dst_sel:DWORD dst_unused:UNUSED_PAD src0_sel:DWORD src1_sel:WORD_1
	v_or_b32_sdwa v44, v44, v43 dst_sel:DWORD dst_unused:UNUSED_PAD src0_sel:DWORD src1_sel:WORD_1
	global_store_dwordx2 v[40:41], v[44:45], off offset:96
	v_exp_f32_e32 v44, v114
	v_exp_f32_e32 v45, v112
	v_exp_f32_e32 v46, v115
	v_exp_f32_e32 v47, v113
	v_or_b32_e32 v40, 16, v42
	v_pk_add_f32 v[44:45], v[44:45], 1.0 op_sel_hi:[1,0]
	v_mad_i64_i32 v[40:41], s[6:7], v40, s67, v[74:75]
	v_div_scale_f32 v43, s[6:7], v44, v44, 1.0
	v_rcp_f32_e32 v48, v43
	v_lshl_add_u64 v[40:41], v[40:41], 0, v[96:97]
	v_mul_f32_e32 v37, 0xbfb8aa3b, v37
	v_mul_f32_e32 v36, 0xbfb8aa3b, v36
	v_fma_f32 v49, -v43, v48, 1.0
	v_fmac_f32_e32 v48, v49, v48
	v_div_scale_f32 v49, vcc, 1.0, v44, 1.0
	v_mul_f32_e32 v50, v49, v48
	v_fma_f32 v51, -v43, v50, v49
	v_fmac_f32_e32 v50, v51, v48
	v_fma_f32 v43, -v43, v50, v49
	v_div_fmas_f32 v43, v43, v48, v50
	v_div_fixup_f32 v43, v43, v44, 1.0
	v_div_scale_f32 v44, s[6:7], v45, v45, 1.0
	v_rcp_f32_e32 v48, v44
	v_exp_f32_e32 v36, v36
	v_mul_f32_e32 v33, 0xbfb8aa3b, v33
	v_mul_f32_e32 v32, 0xbfb8aa3b, v32
	v_fma_f32 v49, -v44, v48, 1.0
	v_fmac_f32_e32 v48, v49, v48
	v_div_scale_f32 v49, vcc, 1.0, v45, 1.0
	v_mul_f32_e32 v50, v49, v48
	v_fma_f32 v51, -v44, v50, v49
	v_fmac_f32_e32 v50, v51, v48
	v_fma_f32 v44, -v44, v50, v49
	v_div_fmas_f32 v44, v44, v48, v50
	v_div_fixup_f32 v48, v44, v45, 1.0
	v_pk_add_f32 v[44:45], v[46:47], 1.0 op_sel_hi:[1,0]
	v_exp_f32_e32 v32, v32
	v_div_scale_f32 v46, s[6:7], v44, v44, 1.0
	v_rcp_f32_e32 v47, v46
	s_nop 0
	v_fma_f32 v49, -v46, v47, 1.0
	v_fmac_f32_e32 v47, v49, v47
	v_div_scale_f32 v49, vcc, 1.0, v44, 1.0
	v_mul_f32_e32 v50, v49, v47
	v_fma_f32 v51, -v46, v50, v49
	v_fmac_f32_e32 v50, v51, v47
	v_fma_f32 v46, -v46, v50, v49
	v_div_fmas_f32 v46, v46, v47, v50
	v_div_fixup_f32 v44, v46, v44, 1.0
	v_div_scale_f32 v46, s[6:7], v45, v45, 1.0
	v_rcp_f32_e32 v47, v46
	s_nop 0
	v_fma_f32 v49, -v46, v47, 1.0
	v_fmac_f32_e32 v47, v49, v47
	v_div_scale_f32 v49, vcc, 1.0, v45, 1.0
	v_mul_f32_e32 v50, v49, v47
	v_fma_f32 v51, -v46, v50, v49
	v_fmac_f32_e32 v50, v51, v47
	v_fma_f32 v46, -v46, v50, v49
	v_div_fmas_f32 v46, v46, v47, v50
	v_div_fixup_f32 v45, v46, v45, 1.0
	v_and_b32_sdwa v46, v48, v154 dst_sel:DWORD dst_unused:UNUSED_PAD src0_sel:WORD_1 src1_sel:DWORD
	v_and_b32_sdwa v47, v43, v154 dst_sel:DWORD dst_unused:UNUSED_PAD src0_sel:WORD_1 src1_sel:DWORD
	v_add3_u32 v43, v43, v47, s33
	v_add3_u32 v46, v48, v46, s33
	v_and_b32_sdwa v47, v45, v154 dst_sel:DWORD dst_unused:UNUSED_PAD src0_sel:WORD_1 src1_sel:DWORD
	v_and_b32_sdwa v48, v44, v154 dst_sel:DWORD dst_unused:UNUSED_PAD src0_sel:WORD_1 src1_sel:DWORD
	v_add3_u32 v45, v45, v47, s33
	v_add3_u32 v44, v44, v48, s33
	v_and_b32_e32 v45, 0xffff0000, v45
	v_and_b32_e32 v44, 0xffff0000, v44
	v_or_b32_sdwa v45, v45, v46 dst_sel:DWORD dst_unused:UNUSED_PAD src0_sel:DWORD src1_sel:WORD_1
	v_or_b32_sdwa v44, v44, v43 dst_sel:DWORD dst_unused:UNUSED_PAD src0_sel:DWORD src1_sel:WORD_1
	global_store_dwordx2 v[40:41], v[44:45], off
	v_exp_f32_e32 v44, v110
	v_exp_f32_e32 v45, v67
	v_exp_f32_e32 v46, v111
	v_exp_f32_e32 v47, v109
	v_pk_add_f32 v[44:45], v[44:45], 1.0 op_sel_hi:[1,0]
	s_nop 0
	v_div_scale_f32 v43, s[6:7], v44, v44, 1.0
	v_rcp_f32_e32 v48, v43
	s_nop 0
	v_fma_f32 v49, -v43, v48, 1.0
	v_fmac_f32_e32 v48, v49, v48
	v_div_scale_f32 v49, vcc, 1.0, v44, 1.0
	v_mul_f32_e32 v50, v49, v48
	v_fma_f32 v51, -v43, v50, v49
	v_fmac_f32_e32 v50, v51, v48
	v_fma_f32 v43, -v43, v50, v49
	v_div_fmas_f32 v43, v43, v48, v50
	v_div_fixup_f32 v43, v43, v44, 1.0
	v_div_scale_f32 v44, s[6:7], v45, v45, 1.0
	v_rcp_f32_e32 v48, v44
	s_nop 0
	v_fma_f32 v49, -v44, v48, 1.0
	v_fmac_f32_e32 v48, v49, v48
	v_div_scale_f32 v49, vcc, 1.0, v45, 1.0
	v_mul_f32_e32 v50, v49, v48
	v_fma_f32 v51, -v44, v50, v49
	v_fmac_f32_e32 v50, v51, v48
	v_fma_f32 v44, -v44, v50, v49
	v_div_fmas_f32 v44, v44, v48, v50
	v_div_fixup_f32 v48, v44, v45, 1.0
	v_pk_add_f32 v[44:45], v[46:47], 1.0 op_sel_hi:[1,0]
	s_nop 0
	v_div_scale_f32 v46, s[6:7], v44, v44, 1.0
	v_rcp_f32_e32 v47, v46
	s_nop 0
	v_fma_f32 v49, -v46, v47, 1.0
	v_fmac_f32_e32 v47, v49, v47
	v_div_scale_f32 v49, vcc, 1.0, v44, 1.0
	v_mul_f32_e32 v50, v49, v47
	v_fma_f32 v51, -v46, v50, v49
	v_fmac_f32_e32 v50, v51, v47
	v_fma_f32 v46, -v46, v50, v49
	v_div_fmas_f32 v46, v46, v47, v50
	v_div_fixup_f32 v44, v46, v44, 1.0
	v_div_scale_f32 v46, s[6:7], v45, v45, 1.0
	v_rcp_f32_e32 v47, v46
	s_nop 0
	v_fma_f32 v49, -v46, v47, 1.0
	v_fmac_f32_e32 v47, v49, v47
	v_div_scale_f32 v49, vcc, 1.0, v45, 1.0
	v_mul_f32_e32 v50, v49, v47
	v_fma_f32 v51, -v46, v50, v49
	v_fmac_f32_e32 v50, v51, v47
	v_fma_f32 v46, -v46, v50, v49
	v_div_fmas_f32 v46, v46, v47, v50
	v_div_fixup_f32 v45, v46, v45, 1.0
	v_and_b32_sdwa v46, v48, v154 dst_sel:DWORD dst_unused:UNUSED_PAD src0_sel:WORD_1 src1_sel:DWORD
	v_and_b32_sdwa v47, v43, v154 dst_sel:DWORD dst_unused:UNUSED_PAD src0_sel:WORD_1 src1_sel:DWORD
	v_add3_u32 v43, v43, v47, s33
	v_add3_u32 v46, v48, v46, s33
	v_and_b32_sdwa v47, v45, v154 dst_sel:DWORD dst_unused:UNUSED_PAD src0_sel:WORD_1 src1_sel:DWORD
	v_and_b32_sdwa v48, v44, v154 dst_sel:DWORD dst_unused:UNUSED_PAD src0_sel:WORD_1 src1_sel:DWORD
	v_add3_u32 v45, v45, v47, s33
	v_add3_u32 v44, v44, v48, s33
	v_and_b32_e32 v45, 0xffff0000, v45
	v_and_b32_e32 v44, 0xffff0000, v44
	v_or_b32_sdwa v45, v45, v46 dst_sel:DWORD dst_unused:UNUSED_PAD src0_sel:DWORD src1_sel:WORD_1
	v_or_b32_sdwa v44, v44, v43 dst_sel:DWORD dst_unused:UNUSED_PAD src0_sel:DWORD src1_sel:WORD_1
	global_store_dwordx2 v[40:41], v[44:45], off offset:32
	v_exp_f32_e32 v44, v37
	v_mul_f32_e32 v37, 0xbfb8aa3b, v38
	v_exp_f32_e32 v37, v37
	v_mul_f32_e32 v38, 0xbfb8aa3b, v39
	v_exp_f32_e32 v45, v38
	v_pk_add_f32 v[36:37], v[36:37], 1.0 op_sel_hi:[1,0]
	s_nop 0
	v_div_scale_f32 v38, s[6:7], v36, v36, 1.0
	v_rcp_f32_e32 v39, v38
	s_nop 0
	v_fma_f32 v43, -v38, v39, 1.0
	v_fmac_f32_e32 v39, v43, v39
	v_div_scale_f32 v43, vcc, 1.0, v36, 1.0
	v_mul_f32_e32 v46, v43, v39
	v_fma_f32 v47, -v38, v46, v43
	v_fmac_f32_e32 v46, v47, v39
	v_fma_f32 v38, -v38, v46, v43
	v_div_fmas_f32 v38, v38, v39, v46
	v_div_fixup_f32 v38, v38, v36, 1.0
	v_div_scale_f32 v36, s[6:7], v37, v37, 1.0
	v_rcp_f32_e32 v39, v36
	s_nop 0
	v_fma_f32 v43, -v36, v39, 1.0
	v_fmac_f32_e32 v39, v43, v39
	v_div_scale_f32 v43, vcc, 1.0, v37, 1.0
	v_mul_f32_e32 v46, v43, v39
	v_fma_f32 v47, -v36, v46, v43
	v_fmac_f32_e32 v46, v47, v39
	v_fma_f32 v36, -v36, v46, v43
	v_div_fmas_f32 v36, v36, v39, v46
	v_div_fixup_f32 v39, v36, v37, 1.0
	v_pk_add_f32 v[36:37], v[44:45], 1.0 op_sel_hi:[1,0]
	s_nop 0
	v_div_scale_f32 v43, s[6:7], v36, v36, 1.0
	v_rcp_f32_e32 v44, v43
	s_nop 0
	v_fma_f32 v45, -v43, v44, 1.0
	v_fmac_f32_e32 v44, v45, v44
	v_div_scale_f32 v45, vcc, 1.0, v36, 1.0
	v_mul_f32_e32 v46, v45, v44
	v_fma_f32 v47, -v43, v46, v45
	v_fmac_f32_e32 v46, v47, v44
	v_fma_f32 v43, -v43, v46, v45
	v_div_fmas_f32 v43, v43, v44, v46
	v_div_fixup_f32 v36, v43, v36, 1.0
	v_div_scale_f32 v43, s[6:7], v37, v37, 1.0
	v_rcp_f32_e32 v44, v43
	s_nop 0
	v_fma_f32 v45, -v43, v44, 1.0
	v_fmac_f32_e32 v44, v45, v44
	v_div_scale_f32 v45, vcc, 1.0, v37, 1.0
	v_mul_f32_e32 v46, v45, v44
	v_fma_f32 v47, -v43, v46, v45
	v_fmac_f32_e32 v46, v47, v44
	v_fma_f32 v43, -v43, v46, v45
	v_div_fmas_f32 v43, v43, v44, v46
	v_div_fixup_f32 v37, v43, v37, 1.0
	v_and_b32_sdwa v43, v39, v154 dst_sel:DWORD dst_unused:UNUSED_PAD src0_sel:WORD_1 src1_sel:DWORD
	v_and_b32_sdwa v44, v38, v154 dst_sel:DWORD dst_unused:UNUSED_PAD src0_sel:WORD_1 src1_sel:DWORD
	v_add3_u32 v38, v38, v44, s33
	v_add3_u32 v39, v39, v43, s33
	v_and_b32_sdwa v43, v37, v154 dst_sel:DWORD dst_unused:UNUSED_PAD src0_sel:WORD_1 src1_sel:DWORD
	v_and_b32_sdwa v44, v36, v154 dst_sel:DWORD dst_unused:UNUSED_PAD src0_sel:WORD_1 src1_sel:DWORD
	v_add3_u32 v37, v37, v43, s33
	v_add3_u32 v36, v36, v44, s33
	v_and_b32_e32 v37, 0xffff0000, v37
	v_and_b32_e32 v36, 0xffff0000, v36
	v_or_b32_sdwa v37, v37, v39 dst_sel:DWORD dst_unused:UNUSED_PAD src0_sel:DWORD src1_sel:WORD_1
	v_or_b32_sdwa v36, v36, v38 dst_sel:DWORD dst_unused:UNUSED_PAD src0_sel:DWORD src1_sel:WORD_1
	global_store_dwordx2 v[40:41], v[36:37], off offset:64
	v_exp_f32_e32 v36, v33
	v_mul_f32_e32 v33, 0xbfb8aa3b, v34
	v_exp_f32_e32 v33, v33
	v_mul_f32_e32 v34, 0xbfb8aa3b, v35
	v_exp_f32_e32 v37, v34
	v_pk_add_f32 v[32:33], v[32:33], 1.0 op_sel_hi:[1,0]
	s_nop 0
	v_div_scale_f32 v34, s[6:7], v32, v32, 1.0
	v_rcp_f32_e32 v35, v34
	s_nop 0
	v_fma_f32 v38, -v34, v35, 1.0
	v_fmac_f32_e32 v35, v38, v35
	v_div_scale_f32 v38, vcc, 1.0, v32, 1.0
	v_mul_f32_e32 v39, v38, v35
	v_fma_f32 v43, -v34, v39, v38
	v_fmac_f32_e32 v39, v43, v35
	v_fma_f32 v34, -v34, v39, v38
	v_div_fmas_f32 v34, v34, v35, v39
	v_div_fixup_f32 v34, v34, v32, 1.0
	v_div_scale_f32 v32, s[6:7], v33, v33, 1.0
	v_rcp_f32_e32 v35, v32
	s_nop 0
	v_fma_f32 v38, -v32, v35, 1.0
	v_fmac_f32_e32 v35, v38, v35
	v_div_scale_f32 v38, vcc, 1.0, v33, 1.0
	v_mul_f32_e32 v39, v38, v35
	v_fma_f32 v43, -v32, v39, v38
	v_fmac_f32_e32 v39, v43, v35
	v_fma_f32 v32, -v32, v39, v38
	v_div_fmas_f32 v32, v32, v35, v39
	v_div_fixup_f32 v35, v32, v33, 1.0
	v_pk_add_f32 v[32:33], v[36:37], 1.0 op_sel_hi:[1,0]
	s_nop 0
	v_div_scale_f32 v36, s[6:7], v32, v32, 1.0
	v_rcp_f32_e32 v37, v36
	s_nop 0
	v_fma_f32 v38, -v36, v37, 1.0
	v_fmac_f32_e32 v37, v38, v37
	v_div_scale_f32 v38, vcc, 1.0, v32, 1.0
	v_mul_f32_e32 v39, v38, v37
	v_fma_f32 v43, -v36, v39, v38
	v_fmac_f32_e32 v39, v43, v37
	v_fma_f32 v36, -v36, v39, v38
	v_div_fmas_f32 v36, v36, v37, v39
	v_div_fixup_f32 v32, v36, v32, 1.0
	v_div_scale_f32 v36, s[6:7], v33, v33, 1.0
	v_rcp_f32_e32 v37, v36
	s_nop 0
	v_fma_f32 v38, -v36, v37, 1.0
	v_fmac_f32_e32 v37, v38, v37
	v_div_scale_f32 v38, vcc, 1.0, v33, 1.0
	v_mul_f32_e32 v39, v38, v37
	v_fma_f32 v43, -v36, v39, v38
	v_fmac_f32_e32 v39, v43, v37
	v_fma_f32 v36, -v36, v39, v38
	v_div_fmas_f32 v36, v36, v37, v39
	v_div_fixup_f32 v33, v36, v33, 1.0
	v_and_b32_sdwa v36, v35, v154 dst_sel:DWORD dst_unused:UNUSED_PAD src0_sel:WORD_1 src1_sel:DWORD
	v_and_b32_sdwa v37, v34, v154 dst_sel:DWORD dst_unused:UNUSED_PAD src0_sel:WORD_1 src1_sel:DWORD
	v_add3_u32 v34, v34, v37, s33
	v_add3_u32 v35, v35, v36, s33
	v_and_b32_sdwa v36, v33, v154 dst_sel:DWORD dst_unused:UNUSED_PAD src0_sel:WORD_1 src1_sel:DWORD
	v_and_b32_sdwa v37, v32, v154 dst_sel:DWORD dst_unused:UNUSED_PAD src0_sel:WORD_1 src1_sel:DWORD
	v_add3_u32 v33, v33, v36, s33
	v_add3_u32 v32, v32, v37, s33
	v_and_b32_e32 v33, 0xffff0000, v33
	v_and_b32_e32 v32, 0xffff0000, v32
	v_or_b32_sdwa v33, v33, v35 dst_sel:DWORD dst_unused:UNUSED_PAD src0_sel:DWORD src1_sel:WORD_1
	v_or_b32_sdwa v32, v32, v34 dst_sel:DWORD dst_unused:UNUSED_PAD src0_sel:DWORD src1_sel:WORD_1
	global_store_dwordx2 v[40:41], v[32:33], off offset:96
	v_mul_f32_e32 v28, 0xbfb8aa3b, v28
	v_exp_f32_e32 v34, v28
	v_mul_f32_e32 v28, 0xbfb8aa3b, v29
	v_exp_f32_e32 v36, v28
	v_mul_f32_e32 v28, 0xbfb8aa3b, v30
	v_exp_f32_e32 v35, v28
	v_or_b32_e32 v32, 32, v42
	v_mad_i64_i32 v[32:33], s[6:7], v32, s67, v[74:75]
	v_mul_f32_e32 v28, 0xbfb8aa3b, v31
	v_pk_add_f32 v[30:31], v[34:35], 1.0 op_sel_hi:[1,0]
	v_exp_f32_e32 v37, v28
	v_lshl_add_u64 v[28:29], v[32:33], 0, v[96:97]
	v_div_scale_f32 v32, s[6:7], v30, v30, 1.0
	v_rcp_f32_e32 v33, v32
	v_mul_f32_e32 v25, 0xbfb8aa3b, v25
	v_mul_f32_e32 v24, 0xbfb8aa3b, v24
	v_exp_f32_e32 v24, v24
	v_fma_f32 v34, -v32, v33, 1.0
	v_fmac_f32_e32 v33, v34, v33
	v_div_scale_f32 v34, vcc, 1.0, v30, 1.0
	v_mul_f32_e32 v35, v34, v33
	v_fma_f32 v38, -v32, v35, v34
	v_fmac_f32_e32 v35, v38, v33
	v_fma_f32 v32, -v32, v35, v34
	v_div_fmas_f32 v32, v32, v33, v35
	v_div_fixup_f32 v32, v32, v30, 1.0
	v_div_scale_f32 v30, s[6:7], v31, v31, 1.0
	v_rcp_f32_e32 v33, v30
	v_mul_f32_e32 v21, 0xbfb8aa3b, v21
	v_mul_f32_e32 v20, 0xbfb8aa3b, v20
	v_exp_f32_e32 v20, v20
	v_fma_f32 v34, -v30, v33, 1.0
	v_fmac_f32_e32 v33, v34, v33
	v_div_scale_f32 v34, vcc, 1.0, v31, 1.0
	v_mul_f32_e32 v35, v34, v33
	v_fma_f32 v38, -v30, v35, v34
	v_fmac_f32_e32 v35, v38, v33
	v_fma_f32 v30, -v30, v35, v34
	v_div_fmas_f32 v30, v30, v33, v35
	v_div_fixup_f32 v33, v30, v31, 1.0
	v_pk_add_f32 v[30:31], v[36:37], 1.0 op_sel_hi:[1,0]
	v_mul_f32_e32 v17, 0xbfb8aa3b, v17
	v_div_scale_f32 v34, s[6:7], v30, v30, 1.0
	v_rcp_f32_e32 v35, v34
	v_mul_f32_e32 v16, 0xbfb8aa3b, v16
	v_exp_f32_e32 v16, v16
	v_fma_f32 v36, -v34, v35, 1.0
	v_fmac_f32_e32 v35, v36, v35
	v_div_scale_f32 v36, vcc, 1.0, v30, 1.0
	v_mul_f32_e32 v37, v36, v35
	v_fma_f32 v38, -v34, v37, v36
	v_fmac_f32_e32 v37, v38, v35
	v_fma_f32 v34, -v34, v37, v36
	v_div_fmas_f32 v34, v34, v35, v37
	v_div_fixup_f32 v30, v34, v30, 1.0
	v_div_scale_f32 v34, s[6:7], v31, v31, 1.0
	v_rcp_f32_e32 v35, v34
	s_nop 0
	v_fma_f32 v36, -v34, v35, 1.0
	v_fmac_f32_e32 v35, v36, v35
	v_div_scale_f32 v36, vcc, 1.0, v31, 1.0
	v_mul_f32_e32 v37, v36, v35
	v_fma_f32 v38, -v34, v37, v36
	v_fmac_f32_e32 v37, v38, v35
	v_fma_f32 v34, -v34, v37, v36
	v_div_fmas_f32 v34, v34, v35, v37
	v_div_fixup_f32 v31, v34, v31, 1.0
	v_and_b32_sdwa v34, v33, v154 dst_sel:DWORD dst_unused:UNUSED_PAD src0_sel:WORD_1 src1_sel:DWORD
	v_and_b32_sdwa v35, v32, v154 dst_sel:DWORD dst_unused:UNUSED_PAD src0_sel:WORD_1 src1_sel:DWORD
	v_add3_u32 v32, v32, v35, s33
	v_add3_u32 v33, v33, v34, s33
	v_and_b32_sdwa v34, v31, v154 dst_sel:DWORD dst_unused:UNUSED_PAD src0_sel:WORD_1 src1_sel:DWORD
	v_and_b32_sdwa v35, v30, v154 dst_sel:DWORD dst_unused:UNUSED_PAD src0_sel:WORD_1 src1_sel:DWORD
	v_add3_u32 v31, v31, v34, s33
	v_add3_u32 v30, v30, v35, s33
	v_and_b32_e32 v31, 0xffff0000, v31
	v_and_b32_e32 v30, 0xffff0000, v30
	v_or_b32_sdwa v31, v31, v33 dst_sel:DWORD dst_unused:UNUSED_PAD src0_sel:DWORD src1_sel:WORD_1
	v_or_b32_sdwa v30, v30, v32 dst_sel:DWORD dst_unused:UNUSED_PAD src0_sel:DWORD src1_sel:WORD_1
	global_store_dwordx2 v[28:29], v[30:31], off
	v_exp_f32_e32 v30, v25
	v_mul_f32_e32 v25, 0xbfb8aa3b, v26
	v_exp_f32_e32 v25, v25
	v_mul_f32_e32 v26, 0xbfb8aa3b, v27
	v_exp_f32_e32 v31, v26
	v_pk_add_f32 v[24:25], v[24:25], 1.0 op_sel_hi:[1,0]
	s_nop 0
	v_div_scale_f32 v26, s[6:7], v24, v24, 1.0
	v_rcp_f32_e32 v27, v26
	s_nop 0
	v_fma_f32 v32, -v26, v27, 1.0
	v_fmac_f32_e32 v27, v32, v27
	v_div_scale_f32 v32, vcc, 1.0, v24, 1.0
	v_mul_f32_e32 v33, v32, v27
	v_fma_f32 v34, -v26, v33, v32
	v_fmac_f32_e32 v33, v34, v27
	v_fma_f32 v26, -v26, v33, v32
	v_div_fmas_f32 v26, v26, v27, v33
	v_div_fixup_f32 v26, v26, v24, 1.0
	v_div_scale_f32 v24, s[6:7], v25, v25, 1.0
	v_rcp_f32_e32 v27, v24
	s_nop 0
	v_fma_f32 v32, -v24, v27, 1.0
	v_fmac_f32_e32 v27, v32, v27
	v_div_scale_f32 v32, vcc, 1.0, v25, 1.0
	v_mul_f32_e32 v33, v32, v27
	v_fma_f32 v34, -v24, v33, v32
	v_fmac_f32_e32 v33, v34, v27
	v_fma_f32 v24, -v24, v33, v32
	v_div_fmas_f32 v24, v24, v27, v33
	v_div_fixup_f32 v27, v24, v25, 1.0
	v_pk_add_f32 v[24:25], v[30:31], 1.0 op_sel_hi:[1,0]
	s_nop 0
	v_div_scale_f32 v30, s[6:7], v24, v24, 1.0
	v_rcp_f32_e32 v31, v30
	s_nop 0
	v_fma_f32 v32, -v30, v31, 1.0
	v_fmac_f32_e32 v31, v32, v31
	v_div_scale_f32 v32, vcc, 1.0, v24, 1.0
	v_mul_f32_e32 v33, v32, v31
	v_fma_f32 v34, -v30, v33, v32
	v_fmac_f32_e32 v33, v34, v31
	v_fma_f32 v30, -v30, v33, v32
	v_div_fmas_f32 v30, v30, v31, v33
	v_div_fixup_f32 v24, v30, v24, 1.0
	v_div_scale_f32 v30, s[6:7], v25, v25, 1.0
	v_rcp_f32_e32 v31, v30
	s_nop 0
	v_fma_f32 v32, -v30, v31, 1.0
	v_fmac_f32_e32 v31, v32, v31
	v_div_scale_f32 v32, vcc, 1.0, v25, 1.0
	v_mul_f32_e32 v33, v32, v31
	v_fma_f32 v34, -v30, v33, v32
	v_fmac_f32_e32 v33, v34, v31
	v_fma_f32 v30, -v30, v33, v32
	v_div_fmas_f32 v30, v30, v31, v33
	v_div_fixup_f32 v25, v30, v25, 1.0
	v_and_b32_sdwa v30, v27, v154 dst_sel:DWORD dst_unused:UNUSED_PAD src0_sel:WORD_1 src1_sel:DWORD
	v_and_b32_sdwa v31, v26, v154 dst_sel:DWORD dst_unused:UNUSED_PAD src0_sel:WORD_1 src1_sel:DWORD
	v_add3_u32 v26, v26, v31, s33
	v_add3_u32 v27, v27, v30, s33
	v_and_b32_sdwa v30, v25, v154 dst_sel:DWORD dst_unused:UNUSED_PAD src0_sel:WORD_1 src1_sel:DWORD
	v_and_b32_sdwa v31, v24, v154 dst_sel:DWORD dst_unused:UNUSED_PAD src0_sel:WORD_1 src1_sel:DWORD
	v_add3_u32 v25, v25, v30, s33
	v_add3_u32 v24, v24, v31, s33
	v_and_b32_e32 v25, 0xffff0000, v25
	v_and_b32_e32 v24, 0xffff0000, v24
	v_or_b32_sdwa v25, v25, v27 dst_sel:DWORD dst_unused:UNUSED_PAD src0_sel:DWORD src1_sel:WORD_1
	v_or_b32_sdwa v24, v24, v26 dst_sel:DWORD dst_unused:UNUSED_PAD src0_sel:DWORD src1_sel:WORD_1
	global_store_dwordx2 v[28:29], v[24:25], off offset:32
	v_exp_f32_e32 v24, v21
	v_mul_f32_e32 v21, 0xbfb8aa3b, v22
	v_exp_f32_e32 v21, v21
	v_mul_f32_e32 v22, 0xbfb8aa3b, v23
	v_exp_f32_e32 v25, v22
	v_pk_add_f32 v[20:21], v[20:21], 1.0 op_sel_hi:[1,0]
	s_nop 0
	v_div_scale_f32 v22, s[6:7], v20, v20, 1.0
	v_rcp_f32_e32 v23, v22
	s_nop 0
	v_fma_f32 v26, -v22, v23, 1.0
	v_fmac_f32_e32 v23, v26, v23
	v_div_scale_f32 v26, vcc, 1.0, v20, 1.0
	v_mul_f32_e32 v27, v26, v23
	v_fma_f32 v30, -v22, v27, v26
	v_fmac_f32_e32 v27, v30, v23
	v_fma_f32 v22, -v22, v27, v26
	v_div_fmas_f32 v22, v22, v23, v27
	v_div_fixup_f32 v22, v22, v20, 1.0
	v_div_scale_f32 v20, s[6:7], v21, v21, 1.0
	v_rcp_f32_e32 v23, v20
	s_nop 0
	v_fma_f32 v26, -v20, v23, 1.0
	v_fmac_f32_e32 v23, v26, v23
	v_div_scale_f32 v26, vcc, 1.0, v21, 1.0
	v_mul_f32_e32 v27, v26, v23
	v_fma_f32 v30, -v20, v27, v26
	v_fmac_f32_e32 v27, v30, v23
	v_fma_f32 v20, -v20, v27, v26
	v_div_fmas_f32 v20, v20, v23, v27
	v_div_fixup_f32 v23, v20, v21, 1.0
	v_pk_add_f32 v[20:21], v[24:25], 1.0 op_sel_hi:[1,0]
	s_nop 0
	v_div_scale_f32 v24, s[6:7], v20, v20, 1.0
	v_rcp_f32_e32 v25, v24
	s_nop 0
	v_fma_f32 v26, -v24, v25, 1.0
	v_fmac_f32_e32 v25, v26, v25
	v_div_scale_f32 v26, vcc, 1.0, v20, 1.0
	v_mul_f32_e32 v27, v26, v25
	v_fma_f32 v30, -v24, v27, v26
	v_fmac_f32_e32 v27, v30, v25
	v_fma_f32 v24, -v24, v27, v26
	v_div_fmas_f32 v24, v24, v25, v27
	v_div_fixup_f32 v20, v24, v20, 1.0
	v_div_scale_f32 v24, s[6:7], v21, v21, 1.0
	v_rcp_f32_e32 v25, v24
	s_nop 0
	v_fma_f32 v26, -v24, v25, 1.0
	v_fmac_f32_e32 v25, v26, v25
	v_div_scale_f32 v26, vcc, 1.0, v21, 1.0
	v_mul_f32_e32 v27, v26, v25
	v_fma_f32 v30, -v24, v27, v26
	v_fmac_f32_e32 v27, v30, v25
	v_fma_f32 v24, -v24, v27, v26
	v_div_fmas_f32 v24, v24, v25, v27
	v_div_fixup_f32 v21, v24, v21, 1.0
	v_and_b32_sdwa v24, v23, v154 dst_sel:DWORD dst_unused:UNUSED_PAD src0_sel:WORD_1 src1_sel:DWORD
	v_and_b32_sdwa v25, v22, v154 dst_sel:DWORD dst_unused:UNUSED_PAD src0_sel:WORD_1 src1_sel:DWORD
	v_add3_u32 v22, v22, v25, s33
	v_add3_u32 v23, v23, v24, s33
	v_and_b32_sdwa v24, v21, v154 dst_sel:DWORD dst_unused:UNUSED_PAD src0_sel:WORD_1 src1_sel:DWORD
	v_and_b32_sdwa v25, v20, v154 dst_sel:DWORD dst_unused:UNUSED_PAD src0_sel:WORD_1 src1_sel:DWORD
	v_add3_u32 v21, v21, v24, s33
	v_add3_u32 v20, v20, v25, s33
	v_and_b32_e32 v21, 0xffff0000, v21
	v_and_b32_e32 v20, 0xffff0000, v20
	v_or_b32_sdwa v21, v21, v23 dst_sel:DWORD dst_unused:UNUSED_PAD src0_sel:DWORD src1_sel:WORD_1
	v_or_b32_sdwa v20, v20, v22 dst_sel:DWORD dst_unused:UNUSED_PAD src0_sel:DWORD src1_sel:WORD_1
	global_store_dwordx2 v[28:29], v[20:21], off offset:64
	v_exp_f32_e32 v20, v17
	v_mul_f32_e32 v17, 0xbfb8aa3b, v18
	v_exp_f32_e32 v17, v17
	v_mul_f32_e32 v18, 0xbfb8aa3b, v19
	v_exp_f32_e32 v21, v18
	v_pk_add_f32 v[16:17], v[16:17], 1.0 op_sel_hi:[1,0]
	s_nop 0
	v_div_scale_f32 v18, s[6:7], v16, v16, 1.0
	v_rcp_f32_e32 v19, v18
	s_nop 0
	v_fma_f32 v22, -v18, v19, 1.0
	v_fmac_f32_e32 v19, v22, v19
	v_div_scale_f32 v22, vcc, 1.0, v16, 1.0
	v_mul_f32_e32 v23, v22, v19
	v_fma_f32 v24, -v18, v23, v22
	v_fmac_f32_e32 v23, v24, v19
	v_fma_f32 v18, -v18, v23, v22
	v_div_fmas_f32 v18, v18, v19, v23
	v_div_fixup_f32 v18, v18, v16, 1.0
	v_div_scale_f32 v16, s[6:7], v17, v17, 1.0
	v_rcp_f32_e32 v19, v16
	s_nop 0
	v_fma_f32 v22, -v16, v19, 1.0
	v_fmac_f32_e32 v19, v22, v19
	v_div_scale_f32 v22, vcc, 1.0, v17, 1.0
	v_mul_f32_e32 v23, v22, v19
	v_fma_f32 v24, -v16, v23, v22
	v_fmac_f32_e32 v23, v24, v19
	v_fma_f32 v16, -v16, v23, v22
	v_div_fmas_f32 v16, v16, v19, v23
	v_div_fixup_f32 v19, v16, v17, 1.0
	v_pk_add_f32 v[16:17], v[20:21], 1.0 op_sel_hi:[1,0]
	s_nop 0
	v_div_scale_f32 v20, s[6:7], v16, v16, 1.0
	v_rcp_f32_e32 v21, v20
	s_nop 0
	v_fma_f32 v22, -v20, v21, 1.0
	v_fmac_f32_e32 v21, v22, v21
	v_div_scale_f32 v22, vcc, 1.0, v16, 1.0
	v_mul_f32_e32 v23, v22, v21
	v_fma_f32 v24, -v20, v23, v22
	v_fmac_f32_e32 v23, v24, v21
	v_fma_f32 v20, -v20, v23, v22
	v_div_fmas_f32 v20, v20, v21, v23
	v_div_fixup_f32 v16, v20, v16, 1.0
	v_div_scale_f32 v20, s[6:7], v17, v17, 1.0
	v_rcp_f32_e32 v21, v20
	s_nop 0
	v_fma_f32 v22, -v20, v21, 1.0
	v_fmac_f32_e32 v21, v22, v21
	v_div_scale_f32 v22, vcc, 1.0, v17, 1.0
	v_mul_f32_e32 v23, v22, v21
	v_fma_f32 v24, -v20, v23, v22
	v_fmac_f32_e32 v23, v24, v21
	v_fma_f32 v20, -v20, v23, v22
	v_div_fmas_f32 v20, v20, v21, v23
	v_div_fixup_f32 v17, v20, v17, 1.0
	v_and_b32_sdwa v20, v19, v154 dst_sel:DWORD dst_unused:UNUSED_PAD src0_sel:WORD_1 src1_sel:DWORD
	v_and_b32_sdwa v21, v18, v154 dst_sel:DWORD dst_unused:UNUSED_PAD src0_sel:WORD_1 src1_sel:DWORD
	v_add3_u32 v18, v18, v21, s33
	v_add3_u32 v19, v19, v20, s33
	v_and_b32_sdwa v20, v17, v154 dst_sel:DWORD dst_unused:UNUSED_PAD src0_sel:WORD_1 src1_sel:DWORD
	v_and_b32_sdwa v21, v16, v154 dst_sel:DWORD dst_unused:UNUSED_PAD src0_sel:WORD_1 src1_sel:DWORD
	v_add3_u32 v17, v17, v20, s33
	v_add3_u32 v16, v16, v21, s33
	v_and_b32_e32 v17, 0xffff0000, v17
	v_and_b32_e32 v16, 0xffff0000, v16
	v_or_b32_sdwa v17, v17, v19 dst_sel:DWORD dst_unused:UNUSED_PAD src0_sel:DWORD src1_sel:WORD_1
	v_or_b32_sdwa v16, v16, v18 dst_sel:DWORD dst_unused:UNUSED_PAD src0_sel:DWORD src1_sel:WORD_1
	global_store_dwordx2 v[28:29], v[16:17], off offset:96
	v_mul_f32_e32 v12, 0xbfb8aa3b, v12
	v_exp_f32_e32 v18, v12
	v_mul_f32_e32 v12, 0xbfb8aa3b, v13
	v_exp_f32_e32 v20, v12
	v_mul_f32_e32 v12, 0xbfb8aa3b, v14
	v_exp_f32_e32 v19, v12
	v_or_b32_e32 v16, 48, v42
	v_mad_i64_i32 v[16:17], s[6:7], v16, s67, v[74:75]
	v_mul_f32_e32 v12, 0xbfb8aa3b, v15
	v_pk_add_f32 v[14:15], v[18:19], 1.0 op_sel_hi:[1,0]
	v_exp_f32_e32 v21, v12
	v_lshl_add_u64 v[12:13], v[16:17], 0, v[96:97]
	v_div_scale_f32 v16, s[6:7], v14, v14, 1.0
	v_rcp_f32_e32 v17, v16
	v_mul_f32_e32 v9, 0xbfb8aa3b, v9
	v_mul_f32_e32 v8, 0xbfb8aa3b, v8
	v_exp_f32_e32 v8, v8
	v_fma_f32 v18, -v16, v17, 1.0
	v_fmac_f32_e32 v17, v18, v17
	v_div_scale_f32 v18, vcc, 1.0, v14, 1.0
	v_mul_f32_e32 v19, v18, v17
	v_fma_f32 v22, -v16, v19, v18
	v_fmac_f32_e32 v19, v22, v17
	v_fma_f32 v16, -v16, v19, v18
	v_div_fmas_f32 v16, v16, v17, v19
	v_div_fixup_f32 v16, v16, v14, 1.0
	v_div_scale_f32 v14, s[6:7], v15, v15, 1.0
	v_rcp_f32_e32 v17, v14
	v_mul_f32_e32 v5, 0xbfb8aa3b, v5
	v_mul_f32_e32 v4, 0xbfb8aa3b, v4
	v_exp_f32_e32 v4, v4
	v_fma_f32 v18, -v14, v17, 1.0
	v_fmac_f32_e32 v17, v18, v17
	v_div_scale_f32 v18, vcc, 1.0, v15, 1.0
	v_mul_f32_e32 v19, v18, v17
	v_fma_f32 v22, -v14, v19, v18
	v_fmac_f32_e32 v19, v22, v17
	v_fma_f32 v14, -v14, v19, v18
	v_div_fmas_f32 v14, v14, v17, v19
	v_div_fixup_f32 v17, v14, v15, 1.0
	v_pk_add_f32 v[14:15], v[20:21], 1.0 op_sel_hi:[1,0]
	v_mul_f32_e32 v0, 0xbfb8aa3b, v0
	v_div_scale_f32 v18, s[6:7], v14, v14, 1.0
	v_rcp_f32_e32 v19, v18
	v_exp_f32_e32 v0, v0
	v_fma_f32 v20, -v18, v19, 1.0
	v_fmac_f32_e32 v19, v20, v19
	v_div_scale_f32 v20, vcc, 1.0, v14, 1.0
	v_mul_f32_e32 v21, v20, v19
	v_fma_f32 v22, -v18, v21, v20
	v_fmac_f32_e32 v21, v22, v19
	v_fma_f32 v18, -v18, v21, v20
	v_div_fmas_f32 v18, v18, v19, v21
	v_div_fixup_f32 v14, v18, v14, 1.0
	v_div_scale_f32 v18, s[6:7], v15, v15, 1.0
	v_rcp_f32_e32 v19, v18
	v_add_f32_e32 v0, 1.0, v0
	v_fma_f32 v20, -v18, v19, 1.0
	v_fmac_f32_e32 v19, v20, v19
	v_div_scale_f32 v20, vcc, 1.0, v15, 1.0
	v_mul_f32_e32 v21, v20, v19
	v_fma_f32 v22, -v18, v21, v20
	v_fmac_f32_e32 v21, v22, v19
	v_fma_f32 v18, -v18, v21, v20
	v_div_fmas_f32 v18, v18, v19, v21
	v_div_fixup_f32 v15, v18, v15, 1.0
	v_and_b32_sdwa v18, v17, v154 dst_sel:DWORD dst_unused:UNUSED_PAD src0_sel:WORD_1 src1_sel:DWORD
	v_and_b32_sdwa v19, v16, v154 dst_sel:DWORD dst_unused:UNUSED_PAD src0_sel:WORD_1 src1_sel:DWORD
	v_add3_u32 v16, v16, v19, s33
	v_add3_u32 v17, v17, v18, s33
	v_and_b32_sdwa v18, v15, v154 dst_sel:DWORD dst_unused:UNUSED_PAD src0_sel:WORD_1 src1_sel:DWORD
	v_and_b32_sdwa v19, v14, v154 dst_sel:DWORD dst_unused:UNUSED_PAD src0_sel:WORD_1 src1_sel:DWORD
	v_add3_u32 v15, v15, v18, s33
	v_add3_u32 v14, v14, v19, s33
	v_and_b32_e32 v15, 0xffff0000, v15
	v_and_b32_e32 v14, 0xffff0000, v14
	v_or_b32_sdwa v15, v15, v17 dst_sel:DWORD dst_unused:UNUSED_PAD src0_sel:DWORD src1_sel:WORD_1
	v_or_b32_sdwa v14, v14, v16 dst_sel:DWORD dst_unused:UNUSED_PAD src0_sel:DWORD src1_sel:WORD_1
	global_store_dwordx2 v[12:13], v[14:15], off
	v_exp_f32_e32 v14, v9
	v_mul_f32_e32 v9, 0xbfb8aa3b, v10
	v_exp_f32_e32 v9, v9
	v_mul_f32_e32 v10, 0xbfb8aa3b, v11
	v_exp_f32_e32 v15, v10
	v_pk_add_f32 v[8:9], v[8:9], 1.0 op_sel_hi:[1,0]
	s_nop 0
	v_div_scale_f32 v10, s[6:7], v8, v8, 1.0
	v_rcp_f32_e32 v11, v10
	s_nop 0
	v_fma_f32 v16, -v10, v11, 1.0
	v_fmac_f32_e32 v11, v16, v11
	v_div_scale_f32 v16, vcc, 1.0, v8, 1.0
	v_mul_f32_e32 v17, v16, v11
	v_fma_f32 v18, -v10, v17, v16
	v_fmac_f32_e32 v17, v18, v11
	v_fma_f32 v10, -v10, v17, v16
	v_div_fmas_f32 v10, v10, v11, v17
	v_div_fixup_f32 v10, v10, v8, 1.0
	v_div_scale_f32 v8, s[6:7], v9, v9, 1.0
	v_rcp_f32_e32 v11, v8
	s_nop 0
	v_fma_f32 v16, -v8, v11, 1.0
	v_fmac_f32_e32 v11, v16, v11
	v_div_scale_f32 v16, vcc, 1.0, v9, 1.0
	v_mul_f32_e32 v17, v16, v11
	v_fma_f32 v18, -v8, v17, v16
	v_fmac_f32_e32 v17, v18, v11
	v_fma_f32 v8, -v8, v17, v16
	v_div_fmas_f32 v8, v8, v11, v17
	v_div_fixup_f32 v11, v8, v9, 1.0
	v_pk_add_f32 v[8:9], v[14:15], 1.0 op_sel_hi:[1,0]
	s_nop 0
	v_div_scale_f32 v14, s[6:7], v8, v8, 1.0
	v_rcp_f32_e32 v15, v14
	s_nop 0
	v_fma_f32 v16, -v14, v15, 1.0
	v_fmac_f32_e32 v15, v16, v15
	v_div_scale_f32 v16, vcc, 1.0, v8, 1.0
	v_mul_f32_e32 v17, v16, v15
	v_fma_f32 v18, -v14, v17, v16
	v_fmac_f32_e32 v17, v18, v15
	v_fma_f32 v14, -v14, v17, v16
	v_div_fmas_f32 v14, v14, v15, v17
	v_div_fixup_f32 v8, v14, v8, 1.0
	v_div_scale_f32 v14, s[6:7], v9, v9, 1.0
	v_rcp_f32_e32 v15, v14
	s_nop 0
	v_fma_f32 v16, -v14, v15, 1.0
	v_fmac_f32_e32 v15, v16, v15
	v_div_scale_f32 v16, vcc, 1.0, v9, 1.0
	v_mul_f32_e32 v17, v16, v15
	v_fma_f32 v18, -v14, v17, v16
	v_fmac_f32_e32 v17, v18, v15
	v_fma_f32 v14, -v14, v17, v16
	v_div_fmas_f32 v14, v14, v15, v17
	v_div_fixup_f32 v9, v14, v9, 1.0
	v_and_b32_sdwa v14, v11, v154 dst_sel:DWORD dst_unused:UNUSED_PAD src0_sel:WORD_1 src1_sel:DWORD
	v_and_b32_sdwa v15, v10, v154 dst_sel:DWORD dst_unused:UNUSED_PAD src0_sel:WORD_1 src1_sel:DWORD
	v_add3_u32 v10, v10, v15, s33
	v_add3_u32 v11, v11, v14, s33
	v_and_b32_sdwa v14, v9, v154 dst_sel:DWORD dst_unused:UNUSED_PAD src0_sel:WORD_1 src1_sel:DWORD
	v_and_b32_sdwa v15, v8, v154 dst_sel:DWORD dst_unused:UNUSED_PAD src0_sel:WORD_1 src1_sel:DWORD
	v_add3_u32 v9, v9, v14, s33
	v_add3_u32 v8, v8, v15, s33
	v_and_b32_e32 v9, 0xffff0000, v9
	v_and_b32_e32 v8, 0xffff0000, v8
	v_or_b32_sdwa v9, v9, v11 dst_sel:DWORD dst_unused:UNUSED_PAD src0_sel:DWORD src1_sel:WORD_1
	v_or_b32_sdwa v8, v8, v10 dst_sel:DWORD dst_unused:UNUSED_PAD src0_sel:DWORD src1_sel:WORD_1
	global_store_dwordx2 v[12:13], v[8:9], off offset:32
	v_exp_f32_e32 v8, v5
	v_mul_f32_e32 v5, 0xbfb8aa3b, v6
	v_exp_f32_e32 v5, v5
	v_mul_f32_e32 v6, 0xbfb8aa3b, v7
	v_exp_f32_e32 v9, v6
	v_pk_add_f32 v[4:5], v[4:5], 1.0 op_sel_hi:[1,0]
	s_nop 0
	v_div_scale_f32 v6, s[6:7], v4, v4, 1.0
	v_rcp_f32_e32 v7, v6
	s_nop 0
	v_fma_f32 v10, -v6, v7, 1.0
	v_fmac_f32_e32 v7, v10, v7
	v_div_scale_f32 v10, vcc, 1.0, v4, 1.0
	v_mul_f32_e32 v11, v10, v7
	v_fma_f32 v14, -v6, v11, v10
	v_fmac_f32_e32 v11, v14, v7
	v_fma_f32 v6, -v6, v11, v10
	v_div_fmas_f32 v6, v6, v7, v11
	v_div_fixup_f32 v6, v6, v4, 1.0
	v_div_scale_f32 v4, s[6:7], v5, v5, 1.0
	v_rcp_f32_e32 v7, v4
	s_nop 0
	v_fma_f32 v10, -v4, v7, 1.0
	v_fmac_f32_e32 v7, v10, v7
	v_div_scale_f32 v10, vcc, 1.0, v5, 1.0
	v_mul_f32_e32 v11, v10, v7
	v_fma_f32 v14, -v4, v11, v10
	v_fmac_f32_e32 v11, v14, v7
	v_fma_f32 v4, -v4, v11, v10
	v_div_fmas_f32 v4, v4, v7, v11
	v_div_fixup_f32 v7, v4, v5, 1.0
	v_pk_add_f32 v[4:5], v[8:9], 1.0 op_sel_hi:[1,0]
	s_nop 0
	v_div_scale_f32 v8, s[6:7], v4, v4, 1.0
	v_rcp_f32_e32 v9, v8
	s_nop 0
	v_fma_f32 v10, -v8, v9, 1.0
	v_fmac_f32_e32 v9, v10, v9
	v_div_scale_f32 v10, vcc, 1.0, v4, 1.0
	v_mul_f32_e32 v11, v10, v9
	v_fma_f32 v14, -v8, v11, v10
	v_fmac_f32_e32 v11, v14, v9
	v_fma_f32 v8, -v8, v11, v10
	v_div_fmas_f32 v8, v8, v9, v11
	v_div_fixup_f32 v4, v8, v4, 1.0
	v_div_scale_f32 v8, s[6:7], v5, v5, 1.0
	v_rcp_f32_e32 v9, v8
	s_nop 0
	v_fma_f32 v10, -v8, v9, 1.0
	v_fmac_f32_e32 v9, v10, v9
	v_div_scale_f32 v10, vcc, 1.0, v5, 1.0
	v_mul_f32_e32 v11, v10, v9
	v_fma_f32 v14, -v8, v11, v10
	v_fmac_f32_e32 v11, v14, v9
	v_fma_f32 v8, -v8, v11, v10
	v_div_fmas_f32 v8, v8, v9, v11
	v_div_fixup_f32 v5, v8, v5, 1.0
	v_and_b32_sdwa v8, v7, v154 dst_sel:DWORD dst_unused:UNUSED_PAD src0_sel:WORD_1 src1_sel:DWORD
	v_and_b32_sdwa v9, v6, v154 dst_sel:DWORD dst_unused:UNUSED_PAD src0_sel:WORD_1 src1_sel:DWORD
	v_add3_u32 v6, v6, v9, s33
	v_add3_u32 v7, v7, v8, s33
	v_and_b32_sdwa v8, v5, v154 dst_sel:DWORD dst_unused:UNUSED_PAD src0_sel:WORD_1 src1_sel:DWORD
	v_and_b32_sdwa v9, v4, v154 dst_sel:DWORD dst_unused:UNUSED_PAD src0_sel:WORD_1 src1_sel:DWORD
	v_add3_u32 v5, v5, v8, s33
	v_add3_u32 v4, v4, v9, s33
	v_and_b32_e32 v5, 0xffff0000, v5
	v_and_b32_e32 v4, 0xffff0000, v4
	v_or_b32_sdwa v5, v5, v7 dst_sel:DWORD dst_unused:UNUSED_PAD src0_sel:DWORD src1_sel:WORD_1
	v_or_b32_sdwa v4, v4, v6 dst_sel:DWORD dst_unused:UNUSED_PAD src0_sel:DWORD src1_sel:WORD_1
	global_store_dwordx2 v[12:13], v[4:5], off offset:64
	v_div_scale_f32 v4, s[6:7], v0, v0, 1.0
	v_rcp_f32_e32 v5, v4
	s_nop 0
	v_fma_f32 v6, -v4, v5, 1.0
	v_fmac_f32_e32 v5, v6, v5
	v_div_scale_f32 v6, vcc, 1.0, v0, 1.0
	v_mul_f32_e32 v7, v6, v5
	v_fma_f32 v8, -v4, v7, v6
	v_fmac_f32_e32 v7, v8, v5
	v_fma_f32 v4, -v4, v7, v6
	v_div_fmas_f32 v4, v4, v5, v7
	v_div_fixup_f32 v4, v4, v0, 1.0
	v_mul_f32_e32 v0, 0xbfb8aa3b, v1
	v_exp_f32_e32 v0, v0
	s_nop 0
	v_add_f32_e32 v0, 1.0, v0
	v_div_scale_f32 v1, s[6:7], v0, v0, 1.0
	v_rcp_f32_e32 v5, v1
	s_nop 0
	v_fma_f32 v6, -v1, v5, 1.0
	v_fmac_f32_e32 v5, v6, v5
	v_div_scale_f32 v6, vcc, 1.0, v0, 1.0
	v_mul_f32_e32 v7, v6, v5
	v_fma_f32 v8, -v1, v7, v6
	v_fmac_f32_e32 v7, v8, v5
	v_fma_f32 v1, -v1, v7, v6
	v_div_fmas_f32 v1, v1, v5, v7
	v_div_fixup_f32 v5, v1, v0, 1.0
	v_mul_f32_e32 v0, 0xbfb8aa3b, v2
	v_exp_f32_e32 v1, v0
	v_mul_f32_e32 v0, 0xbfb8aa3b, v3
	v_exp_f32_e32 v0, v0
	v_bfe_u32 v2, v4, 16, 1
	v_add3_u32 v2, v4, v2, s33
	v_bfe_u32 v3, v5, 16, 1
	v_pk_add_f32 v[0:1], v[0:1], 1.0 op_sel_hi:[1,0]
	v_add3_u32 v3, v5, v3, s33
	v_div_scale_f32 v4, s[6:7], v0, v0, 1.0
	v_rcp_f32_e32 v5, v4
	v_lshrrev_b32_e32 v2, 16, v2
	v_fma_f32 v6, -v4, v5, 1.0
	v_fmac_f32_e32 v5, v6, v5
	v_div_scale_f32 v6, vcc, 1.0, v0, 1.0
	v_mul_f32_e32 v7, v6, v5
	v_fma_f32 v8, -v4, v7, v6
	v_fmac_f32_e32 v7, v8, v5
	v_fma_f32 v4, -v4, v7, v6
	v_div_fmas_f32 v4, v4, v5, v7
	v_div_fixup_f32 v0, v4, v0, 1.0
	v_div_scale_f32 v4, s[6:7], v1, v1, 1.0
	v_rcp_f32_e32 v5, v4
	s_mov_b32 s6, 0xffff0000
	v_and_or_b32 v2, v3, s6, v2
	global_store_dword v[12:13], v2, off offset:96
	v_fma_f32 v6, -v4, v5, 1.0
	v_fmac_f32_e32 v5, v6, v5
	v_div_scale_f32 v6, vcc, 1.0, v1, 1.0
	v_mul_f32_e32 v7, v6, v5
	v_fma_f32 v8, -v4, v7, v6
	v_fmac_f32_e32 v7, v8, v5
	v_fma_f32 v4, -v4, v7, v6
	v_div_fmas_f32 v4, v4, v5, v7
	v_div_fixup_f32 v1, v4, v1, 1.0
	v_and_b32_sdwa v4, v1, v154 dst_sel:DWORD dst_unused:UNUSED_PAD src0_sel:WORD_1 src1_sel:DWORD
	v_and_b32_sdwa v5, v0, v154 dst_sel:DWORD dst_unused:UNUSED_PAD src0_sel:WORD_1 src1_sel:DWORD
	v_add3_u32 v1, v1, v4, s33
	v_add3_u32 v0, v0, v5, s33
	v_lshrrev_b32_e32 v1, 16, v1
	v_and_or_b32 v81, v0, s6, v1
	s_mov_b64 s[6:7], 0x60
	v_lshl_add_u64 v[76:77], v[12:13], 0, s[6:7]
